# asymmetric wave priority in scan step loops: waves 4-7 s_setprio 2, waves 0-3 s_setprio 1, so the two waves sharing a SIMD stagger (one steps while the other runs its prologue)
# speedup vs baseline: 1.0454x; 1.0081x over previous
; #define lane LANE_()
; template <int MODE>
; __device__ __forceinline__ void scan_prologue(const ScanP& P, int m0, int seqbase, int T, int h, int d, float* slab, LAS float* lw, float* bon, int lane) {
;     const int fr = lane & 15, fq = lane >> 4, m = m0 + fr, pos = m - seqbase; const bool hp = pos > 0, hn = pos < T - 1;
;     float* srow = slab + fr * 384;
;     f32x4 k4[4], kk4[4], r4[4]; float ss = 0.f;
;     v2u pk_[4][3], pv_[4][3], pr_[4][3];
;     const int offp_ = hp ? -PRP : 0, offn_ = hn ? PRP : 0; const unsigned mp_ = hp ? 0xffffffffu : 0u, mn_ = hn ? 0xffffffffu : 0u;
; #pragma unroll
;     for (int n = 0; n < 4; ++n) { const bf16* p = P.proj + (size_t)m * PRP + h * 64 + 16 * n + 4 * fq;
;         { v2u t; pk_[n][1] = *(const v2u*)(p + 512);
;           t = *(const v2u*)(p + 512 + offp_); pk_[n][0] = (v2u){t.x & mp_, t.y & mp_};
;           t = *(const v2u*)(p + 512 + offn_); pk_[n][2] = (v2u){t.x & mn_, t.y & mn_};
;           if (MODE != 1) { pv_[n][1] = *(const v2u*)(p + 1024);
;             t = *(const v2u*)(p + 1024 + offp_); pv_[n][0] = (v2u){t.x & mp_, t.y & mp_};
;             t = *(const v2u*)(p + 1024 + offn_); pv_[n][2] = (v2u){t.x & mn_, t.y & mn_}; }
;           if (MODE == 2) { pr_[n][1] = *(const v2u*)(p);
;             t = *(const v2u*)(p + offp_); pr_[n][0] = (v2u){t.x & mp_, t.y & mp_};
;             t = *(const v2u*)(p + offn_); pr_[n][2] = (v2u){t.x & mn_, t.y & mn_}; } } }
;     v4u xw_[2]; bf16x8 xa_[2];
; #pragma unroll
;     for (int ks = 0; ks < 2; ++ks) { xw_[ks] = *(const v4u*)(P.proj + (size_t)m * PRP + 1536 + d * 64 + ks * 32 + 8 * fq); xa_[ks] = *(const bf16x8*)(P.proj + (size_t)m * PRP + 1664 + d * 64 + ks * 32 + 8 * fq); }
.LBB0_289:
	s_not_b32 s4, s61
	s_add_i32 s14, s53, s4
	s_and_b64 s[4:5], s[82:83], exec
	s_cselect_b32 s4, s61, s14
	s_lshl_b32 s4, s4, 4
	v_mov_b32_e32 v212, v172
	s_add_i32 s4, s4, s52
	s_lshl_b32 s14, s87, 1
	v_and_b32_e32 v231, 15, v212
	v_or_b32_e32 v128, s4, v231
	s_waitcnt vmcnt(0)
	v_subrev_u32_e32 v129, s86, v128
	v_cmp_lt_i32_e64 s[4:5], 0, v129
	v_cmp_gt_i32_e32 vcc, s49, v129
	v_ashrrev_i32_e32 v129, 31, v128
	v_ashrrev_i32_e32 v138, 4, v212
	v_lshlrev_b64 v[128:129], 12, v[128:129]
	v_lshl_add_u64 v[128:129], s[64:65], 0, v[128:129]
	v_lshlrev_b32_e32 v154, 2, v138
	v_lshl_add_u64 v[132:133], v[128:129], 0, s[14:15]
	v_ashrrev_i32_e32 v155, 31, v154
	v_cndmask_b32_e64 v131, 0, -1, s[4:5]
	v_cndmask_b32_e64 v130, 0, v224, s[4:5]
	v_lshl_add_u64 v[132:133], v[154:155], 1, v[132:133]
	v_lshl_add_u64 v[130:131], v[132:133], 0, v[130:131]
	global_load_dwordx2 v[134:135], v[130:131], off offset:1024
	global_load_dwordx2 v[166:167], v[132:133], off offset:2048
	global_load_dwordx2 v[140:141], v[130:131], off offset:2048
	global_load_dwordx2 v[156:157], v[132:133], off offset:1056
	global_load_dwordx2 v[142:143], v[130:131], off offset:1056
	global_load_dwordx2 v[254:255], v[132:133], off offset:2080
	global_load_dwordx2 v[146:147], v[130:131], off offset:2080
	global_load_dwordx2 v[150:151], v[130:131], off offset:1088
	global_load_dwordx2 v[160:161], v[130:131], off offset:2112
	global_load_dwordx2 v[184:185], v[130:131], off offset:1120
	global_load_dwordx2 v[204:205], v[130:131], off offset:2144
	global_load_dwordx2 v[170:171], v[132:133], off offset:1024
	s_nop 0
	v_cndmask_b32_e32 v180, 0, v219, vcc
	v_mul_u32_u24_e32 v158, 0x180, v231
	s_mov_b32 s85, s15
	v_lshlrev_b32_e32 v164, 3, v138
	v_lshl_add_u64 v[128:129], v[128:129], 0, s[84:85]
	v_ashrrev_i32_e32 v165, 31, v164
	s_mov_b32 s91, 15
	s_waitcnt vmcnt(0)
	v_lshlrev_b32_e32 v240, 16, v170
	v_cndmask_b32_e64 v230, 0, v134, s[4:5]
	v_cndmask_b32_e64 v234, 0, v135, s[4:5]
	v_lshl_add_u64 v[134:135], v[132:133], 0, v[180:181]
	global_load_dwordx2 v[138:139], v[134:135], off offset:2048
	global_load_dwordx2 v[144:145], v[134:135], off offset:1056
	global_load_dwordx2 v[148:149], v[134:135], off offset:2080
	global_load_dwordx2 v[152:153], v[134:135], off offset:1088
	global_load_dwordx2 v[162:163], v[134:135], off offset:2112
	global_load_dwordx2 v[186:187], v[134:135], off offset:1120
	global_load_dwordx2 v[206:207], v[134:135], off offset:2144
	global_load_dwordx2 v[136:137], v[134:135], off offset:1024
	v_lshlrev_b32_e32 v180, 2, v158
	v_lshl_add_u32 v158, v212, 4, s94
	v_lshl_add_u64 v[176:177], s[62:63], 0, v[180:181]
	v_add_u32_e32 v180, 0x3c00, v158
	v_add_u32_e32 v158, s87, v154
	v_ashrrev_i32_e32 v159, 31, v158
	v_lshlrev_b64 v[168:169], 2, v[158:159]
	v_lshl_add_u64 v[158:159], s[8:9], 0, v[168:169]
	v_and_b32_e32 v241, 0xffff0000, v170
	v_lshlrev_b32_e32 v170, 16, v171
	v_and_b32_e32 v171, 0xffff0000, v171
	v_lshlrev_b32_e32 v232, 16, v230
	v_and_b32_e32 v233, 0xffff0000, v230
	v_lshlrev_b32_e32 v238, 16, v234
	v_and_b32_e32 v239, 0xffff0000, v234
	v_lshl_add_u64 v[176:177], v[154:155], 2, v[176:177]
	v_and_b32_e32 v154, -16, v212
	v_add_u32_e32 v234, s94, v154
	v_add_u32_e32 v154, 0x2200, v234
	s_waitcnt vmcnt(0)
	v_cndmask_b32_e32 v237, 0, v136, vcc
	v_cndmask_b32_e32 v242, 0, v137, vcc
	s_nop 0
	s_nop 0
	v_cndmask_b32_e64 v203, 0, v140, s[4:5]
	v_cndmask_b32_e64 v202, 0, v141, s[4:5]
	s_nop 0
	v_lshlrev_b32_e32 v246, 16, v202
	v_and_b32_e32 v247, 0xffff0000, v202
	v_lshlrev_b32_e32 v202, 16, v166
	v_cndmask_b32_e32 v195, 0, v138, vcc
	v_cndmask_b32_e32 v193, 0, v139, vcc
	s_nop 0
	s_nop 0
	v_cndmask_b32_e64 v201, 0, v142, s[4:5]
	v_cndmask_b32_e64 v200, 0, v143, s[4:5]
	s_nop 0
	v_lshlrev_b32_e32 v250, 16, v200
	v_and_b32_e32 v251, 0xffff0000, v200
	v_lshlrev_b32_e32 v200, 16, v156
	v_cndmask_b32_e32 v194, 0, v144, vcc
	v_cndmask_b32_e32 v192, 0, v145, vcc
	s_nop 0
	s_nop 0
	v_cndmask_b32_e64 v189, 0, v146, s[4:5]
	v_cndmask_b32_e64 v188, 0, v147, s[4:5]
	global_load_dwordx2 v[146:147], v[132:133], off offset:2112
	s_nop 0
	v_cndmask_b32_e32 v179, 0, v148, vcc
	v_cndmask_b32_e32 v178, 0, v149, vcc
	global_load_dwordx2 v[148:149], v[132:133], off offset:1088
	s_nop 0
	v_cndmask_b32_e64 v199, 0, v150, s[4:5]
	v_cndmask_b32_e64 v198, 0, v151, s[4:5]
	global_load_dwordx2 v[150:151], v[132:133], off offset:1120
	s_nop 0
	v_cndmask_b32_e32 v191, 0, v152, vcc
	v_cndmask_b32_e32 v190, 0, v153, vcc
	global_load_dwordx2 v[152:153], v[132:133], off offset:2144
	s_nop 0
	s_nop 0
	v_cndmask_b32_e64 v197, 0, v160, s[4:5]
	v_cndmask_b32_e64 v196, 0, v161, s[4:5]
	s_nop 0
	v_cndmask_b32_e32 v183, 0, v162, vcc
	v_cndmask_b32_e32 v182, 0, v163, vcc
	s_nop 0
	s_nop 0
	v_cndmask_b32_e64 v214, 0, v184, s[4:5]
	v_cndmask_b32_e64 v213, 0, v185, s[4:5]
	s_nop 0
	s_nop 0
	s_nop 0
	s_nop 0
	v_lshl_add_u64 v[132:133], v[164:165], 1, v[128:129]
	global_load_dwordx4 v[140:143], v[132:133], off offset:3072
	global_load_dwordx4 v[136:139], v[132:133], off offset:3328
	global_load_dwordx4 v[128:131], v[132:133], off offset:3136
	v_cndmask_b32_e32 v216, 0, v186, vcc
	v_cndmask_b32_e64 v229, 0, v204, s[4:5]
	v_cndmask_b32_e64 v217, 0, v205, s[4:5]
	s_nop 0
	v_add_co_u32_e64 v160, s[4:5], s45, v158
	v_cndmask_b32_e32 v215, 0, v187, vcc
	global_load_dwordx4 v[184:187], v[158:159], off offset:2048
	s_nop 0
	v_addc_co_u32_e64 v161, s[4:5], 0, v159, s[4:5]
	v_add_co_u32_e64 v162, s[4:5], s96, v158
	v_cndmask_b32_e32 v236, 0, v206, vcc
	v_cndmask_b32_e32 v235, 0, v207, vcc
	global_load_dwordx4 v[204:207], v[160:161], off
	s_nop 0
	s_nop 0
	s_nop 0
	s_nop 0
	global_load_dwordx4 v[132:135], v[132:133], off offset:3392
	s_nop 0
	s_nop 0
	v_addc_co_u32_e64 v163, s[4:5], 0, v159, s[4:5]
	global_load_dwordx4 v[208:211], v[162:163], off offset:2048
	v_cmp_eq_u32_e32 vcc, s88, v231
	s_waitcnt vmcnt(2)
; #define LAS __attribute__((address_space(3)))
; #define lane LANE_()
; template <int MODE>
; __device__ __forceinline__ void scan_prologue(const ScanP& P, int m0, int seqbase, int T, int h, int d, float* slab, LAS float* lw, float* bon, int lane) {
;     ...
; #pragma unroll
;     for (int n = 0; n < 4; ++n) { const int c = 16 * n + 4 * fq, col = h * 64 + c;
;         k4[n] = CONV3_(pk_, 1);
;         if (MODE != 1) { const f32x4 v4 = CONV3_(pv_, 2); *(f32x4*)(srow + 320 + c) = v4; LAS float* xsel = (fr == (d ? 15 : 0)) ? lw + 2048 + c : lw + 2304 + lane * 4; *(LAS f32x4*)(xsel + 192) = v4; }
;         if (MODE == 2) { r4[n] = CONV3_(pr_, 0); *(LAS f32x4*)(lw + 1024 + fr * 64 + c) = r4[n]; }
;         kk4[n] = k4[n] * *(const f32x4*)(P.k_k + col);
;         ss += (kk4[n].x * kk4[n].x + kk4[n].y * kk4[n].y) + (kk4[n].z * kk4[n].z + kk4[n].w * kk4[n].w); }
	v_pk_mul_f32 v[170:171], v[206:207], v[170:171]
	v_pk_mul_f32 v[204:205], v[204:205], v[240:241]
	v_pk_fma_f32 v[170:171], v[186:187], v[238:239], v[170:171]
	v_pk_fma_f32 v[184:185], v[184:185], v[232:233], v[204:205]
	v_lshlrev_b32_e32 v204, 16, v242
	v_and_b32_e32 v205, 0xffff0000, v242
	v_lshlrev_b32_e32 v186, 16, v237
	v_and_b32_e32 v187, 0xffff0000, v237
	s_waitcnt vmcnt(0)
	v_pk_fma_f32 v[204:205], v[210:211], v[204:205], v[170:171]
	v_lshl_add_u64 v[170:171], s[80:81], 0, v[168:169]
	v_pk_fma_f32 v[206:207], v[208:209], v[186:187], v[184:185]
	global_load_dwordx4 v[208:211], v[170:171], off
	v_add_co_u32_e64 v184, s[4:5], s26, v170
	s_nop 0
	s_nop 0
	v_addc_co_u32_e64 v185, s[4:5], 0, v171, s[4:5]
	global_load_dwordx4 v[238:241], v[184:185], off offset:2048
	v_add_co_u32_e64 v186, s[4:5], s96, v170
	v_lshlrev_b32_e32 v232, 16, v203
	s_nop 0
	v_addc_co_u32_e64 v187, s[4:5], 0, v171, s[4:5]
	global_load_dwordx4 v[242:245], v[186:187], off
	v_and_b32_e32 v233, 0xffff0000, v203
	v_and_b32_e32 v203, 0xffff0000, v166
	v_lshlrev_b32_e32 v166, 16, v167
	v_and_b32_e32 v167, 0xffff0000, v167
	s_mov_b32 s4, 0
	s_waitcnt vmcnt(1)
	v_pk_mul_f32 v[166:167], v[240:241], v[166:167]
	v_pk_mul_f32 v[202:203], v[238:239], v[202:203]
	v_pk_fma_f32 v[166:167], v[210:211], v[246:247], v[166:167]
	global_load_dwordx4 v[246:249], v[162:163], off offset:2112
	v_pk_fma_f32 v[202:203], v[208:209], v[232:233], v[202:203]
	v_lshlrev_b32_e32 v208, 16, v195
	v_and_b32_e32 v209, 0xffff0000, v195
	v_lshlrev_b32_e32 v210, 16, v193
	v_and_b32_e32 v211, 0xffff0000, v193
	s_waitcnt vmcnt(1)
	v_pk_fma_f32 v[210:211], v[244:245], v[210:211], v[166:167]
	v_pk_fma_f32 v[208:209], v[242:243], v[208:209], v[202:203]
	global_load_dwordx4 v[242:245], v[160:161], off offset:64
	s_nop 0
	global_store_dwordx4 v[176:177], v[208:211], off offset:1280
	v_cndmask_b32_e32 v233, v180, v154, vcc
	v_lshl_add_u64 v[154:155], s[72:73], 0, v[168:169]
	global_load_dwordx4 v[238:241], v[154:155], off
	ds_write_b128 v233, v[208:211] offset:768
	v_and_b32_e32 v195, 0xffff0000, v192
	s_waitcnt vmcnt(0)
	v_pk_mul_f32 v[208:209], v[204:205], v[240:241]
	v_pk_mul_f32 v[210:211], v[206:207], v[238:239]
	v_pk_mul_f32 v[166:167], v[208:209], v[208:209]
	v_pk_mul_f32 v[202:203], v[210:211], v[210:211]
	s_nop 0
	v_pk_mov_b32 v[238:239], v[202:203], v[166:167] op_sel:[1,0]
	v_mov_b32_e32 v203, v167
	v_pk_add_f32 v[166:167], v[238:239], v[202:203]
	global_load_dwordx4 v[238:241], v[158:159], off offset:2112
	v_lshlrev_b32_e32 v202, 16, v201
	v_and_b32_e32 v203, 0xffff0000, v201
	v_and_b32_e32 v201, 0xffff0000, v156
	v_lshlrev_b32_e32 v156, 16, v157
	v_and_b32_e32 v157, 0xffff0000, v157
	v_pk_mul_f32 v[156:157], v[244:245], v[156:157]
	v_pk_mul_f32 v[200:201], v[242:243], v[200:201]
	global_load_dwordx4 v[242:245], v[186:187], off offset:64
	s_waitcnt vmcnt(1)
	v_pk_fma_f32 v[156:157], v[240:241], v[250:251], v[156:157]
	v_pk_fma_f32 v[200:201], v[238:239], v[202:203], v[200:201]
	global_load_dwordx4 v[238:241], v[184:185], off offset:2112
	v_lshlrev_b32_e32 v202, 16, v194
	v_and_b32_e32 v203, 0xffff0000, v194
	v_lshlrev_b32_e32 v194, 16, v192
	v_pk_fma_f32 v[192:193], v[248:249], v[194:195], v[156:157]
	global_load_dwordx4 v[248:251], v[170:171], off offset:64
	v_pk_fma_f32 v[194:195], v[246:247], v[202:203], v[200:201]
	v_lshlrev_b32_e32 v156, 16, v189
	v_and_b32_e32 v157, 0xffff0000, v189
	v_lshlrev_b32_e32 v246, 16, v188
	v_and_b32_e32 v247, 0xffff0000, v188
	v_lshlrev_b32_e32 v188, 16, v254
	v_and_b32_e32 v189, 0xffff0000, v254
	v_lshlrev_b32_e32 v144, 16, v255
	v_and_b32_e32 v145, 0xffff0000, v255
	s_waitcnt vmcnt(1)
	v_pk_mul_f32 v[144:145], v[240:241], v[144:145]
	v_pk_mul_f32 v[188:189], v[238:239], v[188:189]
	global_load_dwordx4 v[238:241], v[154:155], off offset:64
	s_waitcnt vmcnt(1)
	v_pk_fma_f32 v[144:145], v[250:251], v[246:247], v[144:145]
	v_pk_fma_f32 v[156:157], v[248:249], v[156:157], v[188:189]
	global_load_dwordx4 v[246:249], v[162:163], off offset:2176
	v_lshlrev_b32_e32 v188, 16, v179
	v_and_b32_e32 v189, 0xffff0000, v179
	v_lshlrev_b32_e32 v200, 16, v178
	v_and_b32_e32 v201, 0xffff0000, v178
	v_pk_fma_f32 v[202:203], v[244:245], v[200:201], v[144:145]
	v_pk_fma_f32 v[200:201], v[242:243], v[188:189], v[156:157]
	global_load_dwordx4 v[242:245], v[160:161], off offset:128
	s_nop 0
	global_store_dwordx4 v[176:177], v[200:203], off offset:1344
	s_nop 0
	v_add_u32_e32 v144, 0x2240, v234
	v_cndmask_b32_e32 v232, v180, v144, vcc
	ds_write_b128 v232, v[200:203] offset:768
	s_waitcnt vmcnt(3)
	v_pk_mul_f32 v[200:201], v[192:193], v[240:241]
	v_pk_mul_f32 v[202:203], v[194:195], v[238:239]
	global_load_dwordx4 v[238:241], v[158:159], off offset:2176
	s_nop 0
	s_nop 0
	v_pk_mul_f32 v[144:145], v[200:201], v[200:201]
	v_pk_mul_f32 v[156:157], v[202:203], v[202:203]
	s_nop 0
	v_pk_mov_b32 v[178:179], v[156:157], v[144:145] op_sel:[1,0]
	v_mov_b32_e32 v157, v145
	v_pk_add_f32 v[250:251], v[178:179], v[156:157]
	v_lshlrev_b32_e32 v178, 16, v148
	v_and_b32_e32 v179, 0xffff0000, v148
	v_lshlrev_b32_e32 v148, 16, v149
	v_and_b32_e32 v149, 0xffff0000, v149
	v_lshlrev_b32_e32 v144, 16, v199
	v_and_b32_e32 v145, 0xffff0000, v199
	v_lshlrev_b32_e32 v156, 16, v198
	v_and_b32_e32 v157, 0xffff0000, v198
	s_waitcnt vmcnt(2)
	v_pk_mul_f32 v[148:149], v[244:245], v[148:149]
	v_pk_mul_f32 v[178:179], v[242:243], v[178:179]
	global_load_dwordx4 v[242:245], v[184:185], off offset:2176
	s_waitcnt vmcnt(1)
; #define LAS __attribute__((address_space(3)))
; __device__ __forceinline__ float shx(float v, int o, int lane) { return __builtin_bit_cast(float, __builtin_amdgcn_ds_bpermute((lane ^ o) << 2, __builtin_bit_cast(int, v))); }
; #define lane LANE_()
; template <int MODE>
; __device__ __forceinline__ void scan_prologue(const ScanP& P, int m0, int seqbase, int T, int h, int d, float* slab, LAS float* lw, float* bon, int lane) {
;     ...
;     for (int n = 0; n < 4; ++n) { const int c = 16 * n + 4 * fq, col = h * 64 + c;
;         k4[n] = CONV3_(pk_, 1);
;         if (MODE != 1) { const f32x4 v4 = CONV3_(pv_, 2); *(f32x4*)(srow + 320 + c) = v4; LAS float* xsel = (fr == (d ? 15 : 0)) ? lw + 2048 + c : lw + 2304 + lane * 4; *(LAS f32x4*)(xsel + 192) = v4; }
;         if (MODE == 2) { r4[n] = CONV3_(pr_, 0); *(LAS f32x4*)(lw + 1024 + fr * 64 + c) = r4[n]; }
;         kk4[n] = k4[n] * *(const f32x4*)(P.k_k + col);
;         ss += (kk4[n].x * kk4[n].x + kk4[n].y * kk4[n].y) + (kk4[n].z * kk4[n].z + kk4[n].w * kk4[n].w); }
;     ...
;     ss += shx(ss, 16, lane); ss += shx(ss, 32, lane);
	v_pk_fma_f32 v[148:149], v[240:241], v[156:157], v[148:149]
	v_pk_fma_f32 v[144:145], v[238:239], v[144:145], v[178:179]
	global_load_dwordx4 v[238:241], v[170:171], off offset:128
	v_lshlrev_b32_e32 v156, 16, v191
	v_and_b32_e32 v157, 0xffff0000, v191
	v_lshlrev_b32_e32 v178, 16, v190
	v_and_b32_e32 v179, 0xffff0000, v190
	v_pk_fma_f32 v[188:189], v[248:249], v[178:179], v[148:149]
	v_pk_fma_f32 v[190:191], v[246:247], v[156:157], v[144:145]
	global_load_dwordx4 v[246:249], v[186:187], off offset:128
	v_lshlrev_b32_e32 v156, 16, v146
	v_and_b32_e32 v157, 0xffff0000, v146
	v_lshlrev_b32_e32 v146, 16, v147
	v_and_b32_e32 v147, 0xffff0000, v147
	v_lshlrev_b32_e32 v144, 16, v197
	v_and_b32_e32 v145, 0xffff0000, v197
	v_lshlrev_b32_e32 v148, 16, v196
	v_and_b32_e32 v149, 0xffff0000, v196
	v_lshlrev_b32_e32 v178, 16, v213
	v_and_b32_e32 v179, 0xffff0000, v213
	s_waitcnt vmcnt(2)
	v_pk_mul_f32 v[146:147], v[244:245], v[146:147]
	v_pk_mul_f32 v[156:157], v[242:243], v[156:157]
	global_load_dwordx4 v[242:245], v[154:155], off offset:128
	s_waitcnt vmcnt(2)
	v_pk_fma_f32 v[146:147], v[240:241], v[148:149], v[146:147]
	v_pk_fma_f32 v[144:145], v[238:239], v[144:145], v[156:157]
	global_load_dwordx4 v[238:241], v[158:159], off offset:2240
	v_lshlrev_b32_e32 v148, 16, v183
	v_and_b32_e32 v149, 0xffff0000, v183
	v_lshlrev_b32_e32 v156, 16, v182
	v_and_b32_e32 v157, 0xffff0000, v182
	s_waitcnt vmcnt(2)
	v_pk_fma_f32 v[146:147], v[248:249], v[156:157], v[146:147]
	v_pk_fma_f32 v[144:145], v[246:247], v[148:149], v[144:145]
	global_load_dwordx4 v[246:249], v[160:161], off offset:192
	v_add_u32_e32 v148, 0x2280, v234
	global_store_dwordx4 v[176:177], v[144:147], off offset:1408
	v_cndmask_b32_e32 v230, v180, v148, vcc
	ds_write_b128 v230, v[144:147] offset:768
	s_nop 0
	v_lshlrev_b32_e32 v182, 16, v150
	v_and_b32_e32 v183, 0xffff0000, v150
	v_lshlrev_b32_e32 v150, 16, v151
	v_and_b32_e32 v151, 0xffff0000, v151
	v_lshlrev_b32_e32 v148, 16, v214
	v_and_b32_e32 v149, 0xffff0000, v214
	s_waitcnt vmcnt(3)
	v_pk_mul_f32 v[196:197], v[188:189], v[244:245]
	v_pk_mul_f32 v[198:199], v[190:191], v[242:243]
	global_load_dwordx4 v[242:245], v[162:163], off offset:2240
	s_nop 0
	s_nop 0
	s_nop 0
	s_nop 0
	s_nop 0
	s_waitcnt vmcnt(2)
	v_pk_mul_f32 v[150:151], v[248:249], v[150:151]
	v_pk_mul_f32 v[156:157], v[246:247], v[182:183]
	global_load_dwordx4 v[246:249], v[170:171], off offset:192
	v_pk_fma_f32 v[146:147], v[240:241], v[178:179], v[150:151]
	v_pk_fma_f32 v[144:145], v[238:239], v[148:149], v[156:157]
	global_load_dwordx4 v[238:241], v[184:185], off offset:2240
	global_load_dwordx4 v[156:159], v[186:187], off offset:192
	v_lshlrev_b32_e32 v148, 16, v216
	v_and_b32_e32 v149, 0xffff0000, v216
	v_lshlrev_b32_e32 v150, 16, v215
	v_and_b32_e32 v151, 0xffff0000, v215
	s_waitcnt vmcnt(3)
	v_pk_fma_f32 v[178:179], v[244:245], v[150:151], v[146:147]
	v_pk_fma_f32 v[182:183], v[242:243], v[148:149], v[144:145]
	global_load_dwordx4 v[242:245], v[154:155], off offset:192
	v_lshlrev_b32_e32 v170, 16, v152
	v_and_b32_e32 v171, 0xffff0000, v152
	v_lshlrev_b32_e32 v152, 16, v153
	v_and_b32_e32 v153, 0xffff0000, v153
	v_lshlrev_b32_e32 v160, 16, v229
	v_and_b32_e32 v161, 0xffff0000, v229
	v_lshlrev_b32_e32 v162, 16, v217
	v_and_b32_e32 v163, 0xffff0000, v217
	s_waitcnt vmcnt(2)
	v_pk_mul_f32 v[150:151], v[240:241], v[152:153]
	v_pk_mul_f32 v[148:149], v[238:239], v[170:171]
	v_pk_fma_f32 v[146:147], v[248:249], v[162:163], v[150:151]
	v_pk_fma_f32 v[144:145], v[246:247], v[160:161], v[148:149]
	v_lshlrev_b32_e32 v148, 16, v236
	v_and_b32_e32 v149, 0xffff0000, v236
	v_lshlrev_b32_e32 v150, 16, v235
	v_and_b32_e32 v151, 0xffff0000, v235
	s_waitcnt vmcnt(1)
	v_pk_fma_f32 v[146:147], v[158:159], v[150:151], v[146:147]
	v_pk_fma_f32 v[144:145], v[156:157], v[148:149], v[144:145]
	v_add_u32_e32 v148, 0x22c0, v234
	global_store_dwordx4 v[176:177], v[144:147], off offset:1472
	v_cndmask_b32_e32 v229, v180, v148, vcc
	ds_write_b128 v229, v[144:147] offset:768
	s_nop 0
	v_lshl_or_b32 v180, v231, 6, s89
	s_waitcnt vmcnt(1)
	v_pk_mul_f32 v[186:187], v[182:183], v[242:243]
	v_pk_mul_f32 v[184:185], v[178:179], v[244:245]
	v_mul_f32_e32 v146, v186, v186
	v_pk_add_f32 v[144:145], v[166:167], v[166:167] op_sel:[0,1] op_sel_hi:[1,0]
	v_mul_f32_e32 v148, v187, v187
	v_mov_b32_e32 v145, v146
	v_pk_add_f32 v[146:147], v[250:251], v[250:251] op_sel:[0,1] op_sel_hi:[1,0]
	v_mul_f32_e32 v149, v184, v184
	v_mov_b32_e32 v147, v148
	v_pk_add_f32 v[144:145], v[144:145], v[146:147]
	v_mul_f32_e32 v146, v199, v199
	v_pk_fma_f32 v[146:147], v[198:199], v[198:199], v[146:147] op_sel_hi:[1,1,0]
	v_mul_f32_e32 v148, v197, v197
	v_mul_f32_e32 v150, v185, v185
	v_mov_b32_e32 v147, v149
	v_pk_fma_f32 v[148:149], v[196:197], v[196:197], v[148:149] op_sel_hi:[1,1,0]
	s_nop 0
	v_mov_b32_e32 v149, v150
	v_pk_add_f32 v[146:147], v[146:147], v[148:149]
	s_nop 0
	v_pk_add_f32 v[144:145], v[144:145], v[146:147]
	s_nop 0
	v_add_f32_e32 v144, v144, v145
	v_lshlrev_b32_e32 v145, 2, v212
	v_xor_b32_e32 v146, 64, v145
	ds_bpermute_b32 v146, v146, v144
	v_xor_b32_e32 v145, 0x80, v145
	s_waitcnt lgkmcnt(0)
	v_add_f32_e32 v144, v144, v146
	ds_bpermute_b32 v145, v145, v144
	s_waitcnt lgkmcnt(0)
; __device__ __forceinline__ unsigned pk2(float lo, float hi) { const f2 v = {lo, hi}; return __builtin_bit_cast(unsigned, __builtin_convertvector(v, bf16x2_hw)); }
; __device__ __forceinline__ float tanhf_(float x) { return 1.0f - 2.0f * __builtin_amdgcn_rcpf(1.0f + __builtin_amdgcn_exp2f(2.8853900817779268f * x)); }
; template <int MODE>
; __device__ __forceinline__ void scan_prologue(const ScanP& P, int m0, int seqbase, int T, int h, int d, float* slab, LAS float* lw, float* bon, int lane) {
;     ...
;     const float rs = __builtin_amdgcn_rsqf(ss + 1e-12f);
;     f32x4 Dw[4], Da[4];
; #pragma unroll
;     for (int n = 0; n < 4; ++n) { Dw[n] = (f32x4){0.f, 0.f, 0.f, 0.f}; Da[n] = (f32x4){0.f, 0.f, 0.f, 0.f}; }
; #pragma unroll
;     for (int ks = 0; ks < 2; ++ks) {
;         const v4u xw = xw_[ks]; const bf16x8 xa = xa_[ks];
;         v4u tw;
; #pragma unroll
;         for (int e = 0; e < 4; ++e) tw[e] = pk2(tanhf_(bflo(xw[e])), tanhf_(bfhi(xw[e])));
;         const bf16x8 twv = __builtin_bit_cast(bf16x8, tw);
; #pragma unroll
;         for (int n = 0; n < 4; ++n) { const size_t wo = (size_t)(h * 64 + 16 * n + fr) * 64 + ks * 32 + 8 * fq;
;             Dw[n] = __builtin_amdgcn_mfma_f32_16x16x32_bf16(*(const bf16x8*)(P.upw + wo), twv, Dw[n], 0, 0, 0);
;             Da[n] = __builtin_amdgcn_mfma_f32_16x16x32_bf16(*(const bf16x8*)(P.upa + wo), xa, Da[n], 0, 0, 0); }
;     }
	v_add_f32_e32 v144, v144, v145
	v_add_f32_e32 v212, 0x2b8cbccc, v144
	v_lshlrev_b32_e32 v144, 16, v140
	v_and_b32_e32 v140, 0xffff0000, v140
	v_mul_f32_e32 v140, 0x4038aa3b, v140
	v_exp_f32_e32 v140, v140
	v_mul_f32_e32 v144, 0x4038aa3b, v144
	v_exp_f32_e32 v144, v144
	v_add_f32_e32 v140, 1.0, v140
	v_rcp_f32_e32 v145, v140
	v_lshlrev_b32_e32 v140, 16, v141
	v_and_b32_e32 v141, 0xffff0000, v141
	v_mul_f32_e32 v140, 0x4038aa3b, v140
	v_mul_f32_e32 v141, 0x4038aa3b, v141
	v_exp_f32_e32 v140, v140
	v_exp_f32_e32 v141, v141
	v_add_f32_e32 v144, 1.0, v144
	v_rcp_f32_e32 v144, v144
	v_add_f32_e32 v140, 1.0, v140
	v_add_f32_e32 v141, 1.0, v141
	v_rcp_f32_e32 v140, v140
	v_rcp_f32_e32 v141, v141
	v_pk_fma_f32 v[144:145], v[144:145], 2.0, 1.0 op_sel_hi:[1,0,0] neg_lo:[1,0,0] neg_hi:[1,0,0]
	v_pk_fma_f32 v[140:141], v[140:141], 2.0, 1.0 op_sel_hi:[1,0,0] neg_lo:[1,0,0] neg_hi:[1,0,0]
	s_nop 0
	v_cvt_pk_bf16_f32 v153, v140, v141
	v_lshlrev_b32_e32 v140, 16, v142
	v_and_b32_e32 v141, 0xffff0000, v142
	v_mul_f32_e32 v140, 0x4038aa3b, v140
	v_mul_f32_e32 v141, 0x4038aa3b, v141
	v_exp_f32_e32 v140, v140
	v_exp_f32_e32 v141, v141
	v_cvt_pk_bf16_f32 v152, v144, v145
	v_add_f32_e32 v140, 1.0, v140
	v_add_f32_e32 v141, 1.0, v141
	v_rcp_f32_e32 v140, v140
	v_rcp_f32_e32 v141, v141
	s_nop 0
	v_pk_fma_f32 v[140:141], v[140:141], 2.0, 1.0 op_sel_hi:[1,0,0] neg_lo:[1,0,0] neg_hi:[1,0,0]
	s_nop 0
	v_cvt_pk_bf16_f32 v154, v140, v141
	v_lshlrev_b32_e32 v140, 16, v143
	v_and_b32_e32 v141, 0xffff0000, v143
	v_mul_f32_e32 v140, 0x4038aa3b, v140
	v_mul_f32_e32 v141, 0x4038aa3b, v141
	v_exp_f32_e32 v140, v140
	v_exp_f32_e32 v141, v141
	v_add_f32_e32 v140, 1.0, v140
	v_add_f32_e32 v141, 1.0, v141
	v_rcp_f32_e32 v140, v140
	v_rcp_f32_e32 v141, v141
	s_nop 0
	v_pk_fma_f32 v[140:141], v[140:141], 2.0, 1.0 op_sel_hi:[1,0,0] neg_lo:[1,0,0] neg_hi:[1,0,0]
	s_nop 0
	v_cvt_pk_bf16_f32 v155, v140, v141
	v_lshl_add_u64 v[140:141], v[180:181], 0, v[164:165]
	v_lshlrev_b64 v[144:145], 1, v[140:141]
	v_lshl_add_u64 v[170:171], s[78:79], 0, v[144:145]
	global_load_dwordx4 v[246:249], v[170:171], off
	global_load_dwordx4 v[156:159], v[170:171], off offset:2048
	s_waitcnt vmcnt(0)
	v_mfma_f32_16x16x32_bf16 v[160:163], v[156:159], v[136:139], 0
	v_or_b32_e32 v156, 0x800, v180
	v_mov_b32_e32 v157, v181
	v_lshl_add_u64 v[156:157], v[156:157], 0, v[164:165]
	v_lshlrev_b64 v[236:237], 1, v[156:157]
	v_lshl_add_u64 v[166:167], s[74:75], 0, v[144:145]
	global_load_dwordx4 v[140:143], v[166:167], off
	global_load_dwordx4 v[148:151], v[166:167], off offset:2048
	v_lshl_add_u64 v[156:157], s[74:75], 0, v[236:237]
	global_load_dwordx4 v[144:147], v[156:157], off
	s_nop 0
	s_nop 0
	s_nop 0
	s_nop 0
	s_nop 0
	s_waitcnt vmcnt(0)
	v_mfma_f32_16x16x32_bf16 v[214:217], v[144:147], v[152:155], 0
	v_lshl_add_u64 v[156:157], s[78:79], 0, v[236:237]
	global_load_dwordx4 v[156:159], v[156:157], off
	s_waitcnt vmcnt(0)
	v_mfma_f32_16x16x32_bf16 v[236:239], v[156:159], v[136:139], 0
	v_or_b32_e32 v156, 0xc00, v180
	v_mov_b32_e32 v157, v181
	v_lshl_add_u64 v[156:157], v[156:157], 0, v[164:165]
	v_lshlrev_b64 v[244:245], 1, v[156:157]
	v_lshl_add_u64 v[156:157], s[74:75], 0, v[244:245]
	global_load_dwordx4 v[156:159], v[156:157], off
	v_mfma_f32_16x16x32_bf16 v[140:143], v[140:143], v[152:155], 0
	v_mfma_f32_16x16x32_bf16 v[148:151], v[148:151], v[152:155], 0
	s_waitcnt vmcnt(0)
	v_mfma_f32_16x16x32_bf16 v[240:243], v[156:159], v[152:155], 0
	global_load_dwordx4 v[156:159], v[166:167], off offset:64
	v_lshl_add_u64 v[152:153], s[78:79], 0, v[244:245]
	global_load_dwordx4 v[152:155], v[152:153], off
	v_mfma_f32_16x16x32_bf16 v[144:147], v[246:249], v[136:139], 0
	global_load_dwordx4 v[248:251], v[170:171], off offset:64
	s_waitcnt vmcnt(1)
	v_mfma_f32_16x16x32_bf16 v[244:247], v[152:155], v[136:139], 0
	v_lshlrev_b32_e32 v136, 16, v128
	v_and_b32_e32 v128, 0xffff0000, v128
	v_mul_f32_e32 v136, 0x4038aa3b, v136
	v_mul_f32_e32 v128, 0x4038aa3b, v128
	v_exp_f32_e32 v136, v136
	v_exp_f32_e32 v128, v128
	v_add_f32_e32 v136, 1.0, v136
	v_add_f32_e32 v128, 1.0, v128
	v_rcp_f32_e32 v136, v136
	v_rcp_f32_e32 v137, v128
	s_nop 0
	v_pk_fma_f32 v[136:137], v[136:137], 2.0, 1.0 op_sel_hi:[1,0,0] neg_lo:[1,0,0] neg_hi:[1,0,0]
	s_nop 0
	v_cvt_pk_bf16_f32 v128, v136, v137
	v_lshlrev_b32_e32 v136, 16, v129
	v_and_b32_e32 v129, 0xffff0000, v129
	v_mul_f32_e32 v136, 0x4038aa3b, v136
	v_mul_f32_e32 v129, 0x4038aa3b, v129
	v_exp_f32_e32 v136, v136
	v_exp_f32_e32 v129, v129
	v_add_f32_e32 v136, 1.0, v136
	v_add_f32_e32 v129, 1.0, v129
	v_rcp_f32_e32 v136, v136
	v_rcp_f32_e32 v137, v129
	s_nop 0
	v_pk_fma_f32 v[136:137], v[136:137], 2.0, 1.0 op_sel_hi:[1,0,0] neg_lo:[1,0,0] neg_hi:[1,0,0]
	s_nop 0
	v_cvt_pk_bf16_f32 v129, v136, v137
	v_lshlrev_b32_e32 v136, 16, v130
	v_and_b32_e32 v130, 0xffff0000, v130
	v_mul_f32_e32 v136, 0x4038aa3b, v136
	v_mul_f32_e32 v130, 0x4038aa3b, v130
	v_exp_f32_e32 v136, v136
	v_exp_f32_e32 v130, v130
	v_add_f32_e32 v136, 1.0, v136
	v_add_f32_e32 v130, 1.0, v130
	v_rcp_f32_e32 v136, v136
	v_rcp_f32_e32 v137, v130
	s_nop 0
	v_pk_fma_f32 v[136:137], v[136:137], 2.0, 1.0 op_sel_hi:[1,0,0] neg_lo:[1,0,0] neg_hi:[1,0,0]
	s_nop 0
	v_cvt_pk_bf16_f32 v130, v136, v137
	v_lshlrev_b32_e32 v136, 16, v131
	v_and_b32_e32 v131, 0xffff0000, v131
	v_mul_f32_e32 v136, 0x4038aa3b, v136
	v_mul_f32_e32 v131, 0x4038aa3b, v131
	v_exp_f32_e32 v136, v136
	v_exp_f32_e32 v131, v131
	v_add_f32_e32 v136, 1.0, v136
	v_add_f32_e32 v131, 1.0, v131
	v_rcp_f32_e32 v136, v136
	v_rcp_f32_e32 v137, v131
	s_nop 0
	v_pk_fma_f32 v[136:137], v[136:137], 2.0, 1.0 op_sel_hi:[1,0,0] neg_lo:[1,0,0] neg_hi:[1,0,0]
	s_nop 0
	v_cvt_pk_bf16_f32 v131, v136, v137
	global_load_dwordx4 v[136:139], v[166:167], off offset:2112
	s_nop 0
	v_mfma_f32_16x16x32_bf16 v[152:155], v[156:159], v[128:131], v[140:143]
	global_load_dwordx4 v[140:143], v[170:171], off offset:2112
	s_nop 0
	s_waitcnt vmcnt(2)
; #define LAS __attribute__((address_space(3)))
; __device__ __forceinline__ float sigmoidf_(float x) { return __builtin_amdgcn_rcpf(1.0f + __builtin_amdgcn_exp2f(-1.4426950408889634f * x)); }
; #define lane LANE_()
; template <int MODE>
; __device__ __forceinline__ void scan_prologue(const ScanP& P, int m0, int seqbase, int T, int h, int d, float* slab, LAS float* lw, float* bon, int lane) {
;     ...
;             Dw[n] = __builtin_amdgcn_mfma_f32_16x16x32_bf16(*(const bf16x8*)(P.upw + wo), twv, Dw[n], 0, 0, 0);
;             Da[n] = __builtin_amdgcn_mfma_f32_16x16x32_bf16(*(const bf16x8*)(P.upa + wo), xa, Da[n], 0, 0, 0); }
;     }
;     float bp = 0.f;
; #pragma unroll
;     for (int n = 0; n < 4; ++n) { const int c = 16 * n + 4 * fq, col = h * 64 + c;
;         const f32x4 w0 = *(const f32x4*)(P.w0 + col), a0 = *(const f32x4*)(P.a0 + col), ka = *(const f32x4*)(P.k_a + col);
;         f32x4 wv, bv, kd, av;
; #pragma unroll
;         for (int i = 0; i < 4; ++i) { const float ic = sigmoidf_(Da[n][i] + a0[i]);
;             wv[i] = __builtin_amdgcn_exp2f(-DECAY_SCALE * 1.4426950408889634f * sigmoidf_(Dw[n][i] + w0[i]));
;             const float kk = kk4[n][i] * rs; av[i] = -kk; bv[i] = kk * ic; kd[i] = k4[n][i] * (1.0f + (ic - 1.0f) * ka[i]); }
;         *(LAS f32x4*)(lw + fr * 64 + c) = av; *(LAS f32x4*)(lw + 3072 + fr * 64 + c) = wv; *(LAS f32x4*)(lw + (MODE == 3 ? 1024 : 4096) + fr * 64 + c) = bv;
;         if (MODE != 1) *(f32x4*)(srow + 192 + c) = kd;
;         { LAS float* xsel = (fr == (d ? 15 : 0)) ? lw + 2048 + c : lw + 2304 + lane * 4;
;           if (MODE != 1) *(LAS f32x4*)(xsel + 128) = kd; }
	v_mfma_f32_16x16x32_bf16 v[156:159], v[248:251], v[132:135], v[144:147]
	s_nop 0
	s_waitcnt vmcnt(1)
	v_mfma_f32_16x16x32_bf16 v[144:147], v[136:139], v[128:131], v[148:151]
	s_nop 0
	s_waitcnt vmcnt(0)
	v_mfma_f32_16x16x32_bf16 v[148:151], v[140:143], v[132:135], v[160:163]
	v_or_b32_e32 v136, 0x820, v180
	v_mov_b32_e32 v137, v181
	v_or_b32_e32 v180, 0xc20, v180
	v_lshl_add_u64 v[136:137], v[136:137], 0, v[164:165]
	v_lshl_add_u64 v[160:161], v[180:181], 0, v[164:165]
	v_lshlrev_b64 v[140:141], 1, v[136:137]
	v_lshlrev_b64 v[164:165], 1, v[160:161]
	v_lshl_add_u64 v[136:137], s[74:75], 0, v[140:141]
	global_load_dwordx4 v[248:251], v[136:137], off
	v_lshl_add_u64 v[160:161], s[74:75], 0, v[164:165]
	s_nop 0
	v_lshl_add_u64 v[140:141], s[78:79], 0, v[140:141]
	global_load_dwordx4 v[160:163], v[160:161], off
	v_rsq_f32_e32 v180, v212
	global_load_dwordx4 v[140:143], v[140:141], off
	s_waitcnt vmcnt(2)
	v_mfma_f32_16x16x32_bf16 v[136:139], v[248:251], v[128:131], v[214:217]
	s_nop 2
	v_lshl_add_u64 v[214:215], s[76:77], 0, v[168:169]
	global_load_dwordx4 v[248:251], v[214:215], off
	v_lshl_add_u64 v[212:213], s[10:11], 0, v[168:169]
	v_lshl_add_u64 v[216:217], s[6:7], 0, v[168:169]
	global_load_dwordx4 v[168:171], v[216:217], off
	s_waitcnt vmcnt(3)
	v_mfma_f32_16x16x32_bf16 v[128:131], v[160:163], v[128:131], v[240:243]
	global_load_dwordx4 v[240:243], v[212:213], off
	v_lshl_add_u64 v[160:161], s[78:79], 0, v[164:165]
	global_load_dwordx4 v[160:163], v[160:161], off
	s_nop 0
	s_nop 0
	s_waitcnt vmcnt(4)
	v_mfma_f32_16x16x32_bf16 v[140:143], v[140:143], v[132:135], v[236:239]
	global_load_dwordx4 v[236:239], v[216:217], off offset:64
	s_nop 0
	s_waitcnt vmcnt(4)
	v_add_f32_e32 v156, v156, v248
	s_waitcnt vmcnt(1)
	v_mfma_f32_16x16x32_bf16 v[132:135], v[160:163], v[132:135], v[244:247]
	global_load_dwordx4 v[244:247], v[214:215], off offset:64
	s_nop 0
	v_add_f32_e32 v158, v158, v250
	v_mul_f32_e32 v156, 0xbfb8aa3b, v156
	v_mul_f32_e32 v158, 0xbfb8aa3b, v158
	v_exp_f32_e32 v156, v156
	v_exp_f32_e32 v158, v158
	v_add_f32_e32 v156, 1.0, v156
	v_add_f32_e32 v158, 1.0, v158
	v_rcp_f32_e32 v164, v156
	v_add_f32_e32 v156, v157, v249
	v_rcp_f32_e32 v166, v158
	v_add_f32_e32 v158, v159, v251
	global_load_dwordx4 v[248:251], v[212:213], off offset:64
	v_mul_f32_e32 v156, 0xbfb8aa3b, v156
	v_mul_f32_e32 v158, 0xbfb8aa3b, v158
	v_exp_f32_e32 v156, v156
	v_exp_f32_e32 v158, v158
	v_add_f32_e32 v156, 1.0, v156
	v_add_f32_e32 v158, 1.0, v158
	v_rcp_f32_e32 v165, v156
	v_rcp_f32_e32 v167, v158
	v_add_f32_e32 v152, v152, v240
	v_add_f32_e32 v153, v153, v241
	v_add_f32_e32 v154, v154, v242
	v_add_f32_e32 v155, v155, v243
	global_load_dwordx4 v[240:243], v[212:213], off offset:128
	v_mul_f32_e32 v152, 0xbfb8aa3b, v152
	v_mul_f32_e32 v153, 0xbfb8aa3b, v153
	v_mul_f32_e32 v154, 0xbfb8aa3b, v154
	v_mul_f32_e32 v155, 0xbfb8aa3b, v155
	v_exp_f32_e32 v152, v152
	v_exp_f32_e32 v153, v153
	v_exp_f32_e32 v154, v154
	v_exp_f32_e32 v155, v155
	v_add_f32_e32 v152, 1.0, v152
	v_add_f32_e32 v153, 1.0, v153
	v_add_f32_e32 v154, 1.0, v154
	v_add_f32_e32 v155, 1.0, v155
	v_rcp_f32_e32 v152, v152
	v_rcp_f32_e32 v153, v153
	v_rcp_f32_e32 v154, v154
	v_rcp_f32_e32 v155, v155
	v_mul_f32_e32 v152, 0xbf60028a, v152
	v_mul_f32_e32 v153, 0xbf60028a, v153
	v_pk_mul_f32 v[160:161], v[210:211], v[180:181] op_sel_hi:[1,0]
	v_mul_f32_e32 v154, 0xbf60028a, v154
	v_mul_f32_e32 v155, 0xbf60028a, v155
	v_pk_mul_f32 v[162:163], v[208:209], v[180:181] op_sel_hi:[1,0]
	global_load_dwordx4 v[208:211], v[214:215], off offset:128
	v_exp_f32_e32 v152, v152
	v_exp_f32_e32 v153, v153
	v_xor_b32_e32 v157, 0x80000000, v161
	v_xor_b32_e32 v156, 0x80000000, v160
	v_exp_f32_e32 v154, v154
	v_exp_f32_e32 v155, v155
	v_xor_b32_e32 v158, 0x80000000, v162
	v_xor_b32_e32 v159, 0x80000000, v163
	v_pk_mul_f32 v[160:161], v[160:161], v[164:165]
	v_pk_mul_f32 v[162:163], v[162:163], v[166:167]
	v_pk_add_f32 v[166:167], v[166:167], -1.0 op_sel_hi:[1,0]
	v_pk_add_f32 v[164:165], v[164:165], -1.0 op_sel_hi:[1,0]
	v_pk_fma_f32 v[166:167], v[170:171], v[166:167], 1.0 op_sel_hi:[1,1,0]
	v_pk_fma_f32 v[164:165], v[168:169], v[164:165], 1.0 op_sel_hi:[1,1,0]
	v_pk_mul_f32 v[168:169], v[204:205], v[166:167]
	v_pk_mul_f32 v[166:167], v[206:207], v[164:165]
	global_load_dwordx4 v[204:207], v[216:217], off offset:128
	v_lshl_add_u32 v164, v231, 8, v234
	v_lshl_add_u32 v164, v231, 4, v164
	ds_write_b128 v164, v[156:159]
	ds_write_b128 v164, v[152:155] offset:11520
	ds_write_b128 v164, v[160:163] offset:4352
	global_store_dwordx4 v[176:177], v[166:169], off offset:768
	ds_write_b128 v233, v[166:169] offset:512
	global_load_dwordx4 v[166:169], v[216:217], off offset:192
	s_nop 0
	s_nop 0
	s_nop 0
	s_waitcnt vmcnt(6)
	v_add_f32_e32 v148, v148, v244
	s_waitcnt vmcnt(5)
; #define LAS __attribute__((address_space(3)))
; __device__ __forceinline__ float sigmoidf_(float x) { return __builtin_amdgcn_rcpf(1.0f + __builtin_amdgcn_exp2f(-1.4426950408889634f * x)); }
; #define lane LANE_()
; template <int MODE>
; __device__ __forceinline__ void scan_prologue(const ScanP& P, int m0, int seqbase, int T, int h, int d, float* slab, LAS float* lw, float* bon, int lane) {
;     ...
;     for (int n = 0; n < 4; ++n) { const int c = 16 * n + 4 * fq, col = h * 64 + c;
;         const f32x4 w0 = *(const f32x4*)(P.w0 + col), a0 = *(const f32x4*)(P.a0 + col), ka = *(const f32x4*)(P.k_a + col);
;         f32x4 wv, bv, kd, av;
; #pragma unroll
;         for (int i = 0; i < 4; ++i) { const float ic = sigmoidf_(Da[n][i] + a0[i]);
;             wv[i] = __builtin_amdgcn_exp2f(-DECAY_SCALE * 1.4426950408889634f * sigmoidf_(Dw[n][i] + w0[i]));
;             const float kk = kk4[n][i] * rs; av[i] = -kk; bv[i] = kk * ic; kd[i] = k4[n][i] * (1.0f + (ic - 1.0f) * ka[i]); }
;         *(LAS f32x4*)(lw + fr * 64 + c) = av; *(LAS f32x4*)(lw + 3072 + fr * 64 + c) = wv; *(LAS f32x4*)(lw + (MODE == 3 ? 1024 : 4096) + fr * 64 + c) = bv;
;         if (MODE != 1) *(f32x4*)(srow + 192 + c) = kd;
;         { LAS float* xsel = (fr == (d ? 15 : 0)) ? lw + 2048 + c : lw + 2304 + lane * 4;
;           if (MODE != 1) *(LAS f32x4*)(xsel + 128) = kd; }
;         if (MODE == 2) { const f32x4 rk = *(const f32x4*)(P.r_k + col); const f32x4 t = r4[n] * kd * rk; bp += (t.x + t.y) + (t.z + t.w); }
;         if ((n & 1) == 1) asm volatile("" ::: "memory");
	v_add_f32_e32 v144, v144, v248
	v_add_f32_e32 v145, v145, v249
	v_add_f32_e32 v146, v146, v250
	v_add_f32_e32 v147, v147, v251
	global_load_dwordx4 v[248:251], v[214:215], off offset:192
	v_mul_f32_e32 v144, 0xbfb8aa3b, v144
	v_add_f32_e32 v149, v149, v245
	v_mul_f32_e32 v145, 0xbfb8aa3b, v145
	v_add_f32_e32 v150, v150, v246
	v_mul_f32_e32 v146, 0xbfb8aa3b, v146
	v_add_f32_e32 v151, v151, v247
	global_load_dwordx4 v[244:247], v[212:213], off offset:192
	v_mul_f32_e32 v147, 0xbfb8aa3b, v147
	v_mul_f32_e32 v148, 0xbfb8aa3b, v148
	v_exp_f32_e32 v144, v144
	v_mul_f32_e32 v149, 0xbfb8aa3b, v149
	v_exp_f32_e32 v145, v145
	v_mul_f32_e32 v150, 0xbfb8aa3b, v150
	v_exp_f32_e32 v146, v146
	v_mul_f32_e32 v151, 0xbfb8aa3b, v151
	v_exp_f32_e32 v147, v147
	v_exp_f32_e32 v148, v148
	v_exp_f32_e32 v149, v149
	v_exp_f32_e32 v150, v150
	v_exp_f32_e32 v151, v151
	v_add_f32_e32 v144, 1.0, v144
	v_add_f32_e32 v145, 1.0, v145
	v_add_f32_e32 v146, 1.0, v146
	v_add_f32_e32 v147, 1.0, v147
	v_add_f32_e32 v148, 1.0, v148
	v_rcp_f32_e32 v144, v144
	v_add_f32_e32 v149, 1.0, v149
	v_rcp_f32_e32 v145, v145
	v_add_f32_e32 v150, 1.0, v150
	v_rcp_f32_e32 v146, v146
	v_add_f32_e32 v151, 1.0, v151
	v_rcp_f32_e32 v147, v147
	v_rcp_f32_e32 v148, v148
	v_rcp_f32_e32 v149, v149
	v_rcp_f32_e32 v150, v150
	v_rcp_f32_e32 v151, v151
	v_mul_f32_e32 v144, 0xbf60028a, v144
	v_mul_f32_e32 v145, 0xbf60028a, v145
	v_pk_mul_f32 v[160:161], v[202:203], v[180:181] op_sel_hi:[1,0]
	v_mul_f32_e32 v146, 0xbf60028a, v146
	v_mul_f32_e32 v147, 0xbf60028a, v147
	v_pk_mul_f32 v[162:163], v[200:201], v[180:181] op_sel_hi:[1,0]
	v_exp_f32_e32 v144, v144
	v_exp_f32_e32 v145, v145
	v_xor_b32_e32 v157, 0x80000000, v161
	v_xor_b32_e32 v156, 0x80000000, v160
	v_exp_f32_e32 v146, v146
	v_exp_f32_e32 v147, v147
	v_xor_b32_e32 v158, 0x80000000, v162
	v_xor_b32_e32 v159, 0x80000000, v163
	v_pk_mul_f32 v[160:161], v[160:161], v[148:149]
	v_pk_mul_f32 v[162:163], v[162:163], v[150:151]
	v_pk_add_f32 v[150:151], v[150:151], -1.0 op_sel_hi:[1,0]
	v_pk_add_f32 v[148:149], v[148:149], -1.0 op_sel_hi:[1,0]
	v_pk_fma_f32 v[150:151], v[238:239], v[150:151], 1.0 op_sel_hi:[1,1,0]
	v_pk_fma_f32 v[148:149], v[236:237], v[148:149], 1.0 op_sel_hi:[1,1,0]
	v_pk_mul_f32 v[150:151], v[192:193], v[150:151]
	v_pk_mul_f32 v[148:149], v[194:195], v[148:149]
	ds_write_b128 v164, v[156:159] offset:64
	ds_write_b128 v164, v[144:147] offset:11584
	ds_write_b128 v164, v[160:163] offset:4416
	global_store_dwordx4 v[176:177], v[148:151], off offset:832
	ds_write_b128 v232, v[148:151] offset:512
	s_nop 0
	s_nop 0
	s_nop 0
	s_waitcnt vmcnt(7)
	v_add_f32_e32 v136, v136, v240
	s_waitcnt vmcnt(6)
	v_add_f32_e32 v140, v140, v208
	v_add_f32_e32 v142, v142, v210
	v_mul_f32_e32 v140, 0xbfb8aa3b, v140
	v_mul_f32_e32 v142, 0xbfb8aa3b, v142
	v_exp_f32_e32 v140, v140
	v_exp_f32_e32 v142, v142
	v_add_f32_e32 v137, v137, v241
	v_add_f32_e32 v138, v138, v242
	v_add_f32_e32 v140, 1.0, v140
	v_add_f32_e32 v142, 1.0, v142
	v_add_f32_e32 v139, v139, v243
	v_rcp_f32_e32 v152, v140
	v_mul_f32_e32 v136, 0xbfb8aa3b, v136
	v_add_f32_e32 v140, v141, v209
	v_mul_f32_e32 v137, 0xbfb8aa3b, v137
	v_rcp_f32_e32 v154, v142
	v_mul_f32_e32 v138, 0xbfb8aa3b, v138
	v_add_f32_e32 v142, v143, v211
	v_mul_f32_e32 v139, 0xbfb8aa3b, v139
	v_exp_f32_e32 v136, v136
	v_mul_f32_e32 v140, 0xbfb8aa3b, v140
	v_exp_f32_e32 v137, v137
	v_exp_f32_e32 v138, v138
	v_mul_f32_e32 v142, 0xbfb8aa3b, v142
	v_exp_f32_e32 v139, v139
	v_exp_f32_e32 v140, v140
	v_exp_f32_e32 v142, v142
	v_add_f32_e32 v136, 1.0, v136
	v_add_f32_e32 v137, 1.0, v137
	v_add_f32_e32 v138, 1.0, v138
	v_add_f32_e32 v139, 1.0, v139
	v_rcp_f32_e32 v136, v136
	v_add_f32_e32 v140, 1.0, v140
	v_rcp_f32_e32 v137, v137
	v_rcp_f32_e32 v138, v138
	v_add_f32_e32 v142, 1.0, v142
	v_rcp_f32_e32 v139, v139
	v_rcp_f32_e32 v153, v140
	v_rcp_f32_e32 v155, v142
	v_mul_f32_e32 v136, 0xbf60028a, v136
	v_mul_f32_e32 v137, 0xbf60028a, v137
	v_pk_mul_f32 v[148:149], v[198:199], v[180:181] op_sel_hi:[1,0]
	v_mul_f32_e32 v138, 0xbf60028a, v138
	v_mul_f32_e32 v139, 0xbf60028a, v139
	v_pk_mul_f32 v[150:151], v[196:197], v[180:181] op_sel_hi:[1,0]
	v_exp_f32_e32 v136, v136
	v_exp_f32_e32 v137, v137
	v_xor_b32_e32 v141, 0x80000000, v149
	v_xor_b32_e32 v140, 0x80000000, v148
	v_exp_f32_e32 v138, v138
	v_exp_f32_e32 v139, v139
	v_xor_b32_e32 v142, 0x80000000, v150
	v_xor_b32_e32 v143, 0x80000000, v151
	v_pk_mul_f32 v[148:149], v[148:149], v[152:153]
	v_pk_mul_f32 v[150:151], v[150:151], v[154:155]
	v_pk_add_f32 v[154:155], v[154:155], -1.0 op_sel_hi:[1,0]
	v_pk_add_f32 v[152:153], v[152:153], -1.0 op_sel_hi:[1,0]
	s_waitcnt vmcnt(5)
; #define GAS __attribute__((address_space(1)))
; #define LAS __attribute__((address_space(3)))
; __device__ __forceinline__ float sigmoidf_(float x) { return __builtin_amdgcn_rcpf(1.0f + __builtin_amdgcn_exp2f(-1.4426950408889634f * x)); }
; #define LDS_WAIT() asm volatile("s_waitcnt lgkmcnt(0)" ::: "memory")
; #define lane LANE_()
; template <int MODE>
; __device__ __forceinline__ void scan_prologue(const ScanP& P, int m0, int seqbase, int T, int h, int d, float* slab, LAS float* lw, float* bon, int lane) {
;     ...
;         for (int i = 0; i < 4; ++i) { const float ic = sigmoidf_(Da[n][i] + a0[i]);
;             wv[i] = __builtin_amdgcn_exp2f(-DECAY_SCALE * 1.4426950408889634f * sigmoidf_(Dw[n][i] + w0[i]));
;             const float kk = kk4[n][i] * rs; av[i] = -kk; bv[i] = kk * ic; kd[i] = k4[n][i] * (1.0f + (ic - 1.0f) * ka[i]); }
;         *(LAS f32x4*)(lw + fr * 64 + c) = av; *(LAS f32x4*)(lw + 3072 + fr * 64 + c) = wv; *(LAS f32x4*)(lw + (MODE == 3 ? 1024 : 4096) + fr * 64 + c) = bv;
;         if (MODE != 1) *(f32x4*)(srow + 192 + c) = kd;
;         { LAS float* xsel = (fr == (d ? 15 : 0)) ? lw + 2048 + c : lw + 2304 + lane * 4;
;           if (MODE != 1) *(LAS f32x4*)(xsel + 128) = kd; }
; template <int MODE>
; __device__ __forceinline__ void scan_item(const CAS Args* A, int l, int item, float* slab0, LAS float* ldsw, int lane) {
;     ...
;         LDS_WAIT();
;         float nw[1], nb[1], nk[1], nv[1];
;         { const LAS float* xl = ldsw + 2048 + lane; nw[0] = 0.f; nb[0] = 0.f; nk[0] = 0.f; nv[0] = 0.f; if (MODE != 1) { nk[0] = xl[128]; nv[0] = xl[192]; } }
; #pragma nounroll
;         for (int st = 0; st < 16; ++st) {
;             const int s = d ? 15 - st : st;
;             const float cw = nw[0], cb = nb[0], ck = nk[0], vv = nv[0];
;             if (st < 15) { const GAS float* p = sl + (d ? s - 1 : s + 1) * 384;  if (MODE != 1) { nk[0] = p[192]; nv[0] = p[320]; } }
;             const LAS f32x4* ua = (const LAS f32x4*)(ldsw + s * 64); const LAS f32x4* ur = (const LAS f32x4*)(ldsw + 1024 + s * 64); const LAS f32x4* uw = (const LAS f32x4*)(ldsw + 3072 + s * 64); const LAS f32x4* ub = (const LAS f32x4*)(ldsw + (MODE == 3 ? 1024 : 4096) + s * 64);
	v_pk_fma_f32 v[146:147], v[206:207], v[154:155], 1.0 op_sel_hi:[1,1,0]
	v_pk_fma_f32 v[144:145], v[204:205], v[152:153], 1.0 op_sel_hi:[1,1,0]
	v_pk_mul_f32 v[146:147], v[188:189], v[146:147]
	v_pk_mul_f32 v[144:145], v[190:191], v[144:145]
	ds_write_b128 v164, v[140:143] offset:128
	ds_write_b128 v164, v[136:139] offset:11648
	ds_write_b128 v164, v[148:151] offset:4480
	global_store_dwordx4 v[176:177], v[144:147], off offset:896
	ds_write_b128 v230, v[144:147] offset:512
	s_nop 0
	s_nop 0
	s_nop 0
	s_waitcnt vmcnt(3)
	v_add_f32_e32 v132, v132, v248
	s_waitcnt vmcnt(2)
	v_add_f32_e32 v128, v128, v244
	v_add_f32_e32 v129, v129, v245
	v_add_f32_e32 v130, v130, v246
	v_add_f32_e32 v131, v131, v247
	v_mul_f32_e32 v128, 0xbfb8aa3b, v128
	v_add_f32_e32 v133, v133, v249
	v_mul_f32_e32 v129, 0xbfb8aa3b, v129
	v_add_f32_e32 v134, v134, v250
	v_mul_f32_e32 v130, 0xbfb8aa3b, v130
	v_add_f32_e32 v135, v135, v251
	v_mul_f32_e32 v131, 0xbfb8aa3b, v131
	v_mul_f32_e32 v132, 0xbfb8aa3b, v132
	v_exp_f32_e32 v128, v128
	v_mul_f32_e32 v133, 0xbfb8aa3b, v133
	v_exp_f32_e32 v129, v129
	v_mul_f32_e32 v134, 0xbfb8aa3b, v134
	v_exp_f32_e32 v130, v130
	v_mul_f32_e32 v135, 0xbfb8aa3b, v135
	v_exp_f32_e32 v131, v131
	v_exp_f32_e32 v132, v132
	v_exp_f32_e32 v133, v133
	v_exp_f32_e32 v134, v134
	v_exp_f32_e32 v135, v135
	v_add_f32_e32 v128, 1.0, v128
	v_add_f32_e32 v129, 1.0, v129
	v_add_f32_e32 v130, 1.0, v130
	v_add_f32_e32 v131, 1.0, v131
	v_add_f32_e32 v132, 1.0, v132
	v_rcp_f32_e32 v128, v128
	v_add_f32_e32 v133, 1.0, v133
	v_rcp_f32_e32 v129, v129
	v_add_f32_e32 v134, 1.0, v134
	v_rcp_f32_e32 v130, v130
	v_add_f32_e32 v135, 1.0, v135
	v_rcp_f32_e32 v131, v131
	v_rcp_f32_e32 v132, v132
	v_rcp_f32_e32 v133, v133
	v_rcp_f32_e32 v134, v134
	v_rcp_f32_e32 v135, v135
	v_mul_f32_e32 v128, 0xbf60028a, v128
	v_mul_f32_e32 v129, 0xbf60028a, v129
	v_pk_mul_f32 v[144:145], v[186:187], v[180:181] op_sel_hi:[1,0]
	v_mul_f32_e32 v130, 0xbf60028a, v130
	v_mul_f32_e32 v131, 0xbf60028a, v131
	v_pk_mul_f32 v[146:147], v[184:185], v[180:181] op_sel_hi:[1,0]
	v_exp_f32_e32 v128, v128
	v_exp_f32_e32 v129, v129
	v_xor_b32_e32 v141, 0x80000000, v145
	v_xor_b32_e32 v140, 0x80000000, v144
	v_exp_f32_e32 v130, v130
	v_exp_f32_e32 v131, v131
	v_xor_b32_e32 v142, 0x80000000, v146
	v_xor_b32_e32 v143, 0x80000000, v147
	v_pk_mul_f32 v[144:145], v[144:145], v[132:133]
	v_pk_mul_f32 v[146:147], v[146:147], v[134:135]
	v_pk_add_f32 v[134:135], v[134:135], -1.0 op_sel_hi:[1,0]
	v_pk_add_f32 v[132:133], v[132:133], -1.0 op_sel_hi:[1,0]
	v_pk_fma_f32 v[134:135], v[168:169], v[134:135], 1.0 op_sel_hi:[1,1,0]
	v_pk_fma_f32 v[132:133], v[166:167], v[132:133], 1.0 op_sel_hi:[1,1,0]
	v_pk_mul_f32 v[134:135], v[178:179], v[134:135]
	v_pk_mul_f32 v[132:133], v[182:183], v[132:133]
	ds_write_b128 v164, v[140:143] offset:192
	ds_write_b128 v164, v[128:131] offset:11712
	ds_write_b128 v164, v[144:147] offset:4544
	global_store_dwordx4 v[176:177], v[132:135], off offset:960
	ds_write_b128 v229, v[132:135] offset:512
	s_waitcnt lgkmcnt(0)
	ds_read2st64_b32 v[128:129], v228 offset0:36 offset1:37
	v_subrev_u32_e32 v244, s94, v228
	v_and_b32_e32 v245, 0xc0, v244
	v_and_b32_e32 v244, 60, v244
	v_add_u32_e32 v244, s94, v244
	v_sub_u32_e32 v240, 0, v245
	v_ashrrev_i32_e32 v241, 31, v240
	ds_read_b32 v232, v244 offset:9216
	ds_read_b32 v233, v244 offset:9280
	ds_read_b32 v234, v244 offset:9344
	ds_read_b32 v235, v244 offset:9408
	s_waitcnt lgkmcnt(0)
	v_mov_b32_e32 v130, v129
	s_setprio 1
	s_cmp_lt_u32 s94, 0x14000
	s_cbranch_scc1 .Lprio_a_lo
	s_setprio 2
.Lprio_a_lo:
.LBB0_290:
	s_and_b64 s[92:93], s[82:83], exec
	s_cselect_b32 s5, s4, s91
	s_cmp_eq_u32 s4, 15
	v_mov_b32_e32 v129, v130
	v_mov_b32_e32 v131, v128
	s_cbranch_scc1 .LBB0_292
	s_add_i32 s14, s5, s90
	s_mul_i32 s92, s14, 0x180
	s_ashr_i32 s93, s92, 31
	v_lshl_add_u64 v[132:133], s[92:93], 2, v[174:175]
	v_lshl_add_u64 v[242:243], v[240:241], 0, v[132:133]
	global_load_dword v236, v[242:243], off offset:768
	global_load_dword v237, v[242:243], off offset:832
	global_load_dword v238, v[242:243], off offset:896
	global_load_dword v239, v[242:243], off offset:960
	global_load_dword v129, v[132:133], off offset:1280

; #define GAS __attribute__((address_space(1)))
; #define LAS __attribute__((address_space(3)))
; #define LDS_WAIT() asm volatile("s_waitcnt lgkmcnt(0)" ::: "memory")
; #define lane LANE_()
; template <int MODE>
; __device__ __forceinline__ void scan_item(const CAS Args* A, int l, int item, float* slab0, LAS float* ldsw, int lane) {
;     ...
;         LDS_WAIT();
;         float nw[1], nb[1], nk[1], nv[1];
;         { const LAS float* xl = ldsw + 2048 + lane; nw[0] = 0.f; nb[0] = 0.f; nk[0] = 0.f; nv[0] = 0.f; if (MODE != 1) { nk[0] = xl[128]; nv[0] = xl[192]; } }
; #pragma nounroll
;         for (int st = 0; st < 16; ++st) {
;             const int s = d ? 15 - st : st;
;             const float cw = nw[0], cb = nb[0], ck = nk[0], vv = nv[0];
;             if (st < 15) { const GAS float* p = sl + (d ? s - 1 : s + 1) * 384;  if (MODE != 1) { nk[0] = p[192]; nv[0] = p[320]; } }
;             const LAS f32x4* ua = (const LAS f32x4*)(ldsw + s * 64); const LAS f32x4* ur = (const LAS f32x4*)(ldsw + 1024 + s * 64); const LAS f32x4* uw = (const LAS f32x4*)(ldsw + 3072 + s * 64); const LAS f32x4* ub = (const LAS f32x4*)(ldsw + (MODE == 3 ? 1024 : 4096) + s * 64);
;             f2 sa2 = (f2){0.f, 0.f}, sb2 = (f2){0.f, 0.f}, pa2 = (f2){0.f, 0.f}, pb2 = (f2){0.f, 0.f};
; #pragma unroll
;             for (int j = 0; j < 16; ++j) { const f32x4 aq = ua[j]; const f2 a0 = (f2){aq.x, aq.y}, a1 = (f2){aq.z, aq.w}; sa2 = S[2 * j] * a0 + sa2; sb2 = S[2 * j + 1] * a1 + sb2;
;                 if (MODE == 3) { pa2 = Pm[2 * j] * a0 + pa2; pb2 = Pm[2 * j + 1] * a1 + pb2; } }
;             const float sa = (sa2.x + sa2.y) + (sb2.x + sb2.y), pa = (pa2.x + pa2.y) + (pb2.x + pb2.y); const f2 pas = (f2){pa, pa};
.LBB0_551:
	s_or_b64 exec, exec, s[4:5]
	s_waitcnt lgkmcnt(0)
	s_waitcnt lgkmcnt(0)
	v_subrev_u32_e32 v106, s94, v129
	v_and_b32_e32 v98, 60, v106
	v_add_u32_e32 v98, s94, v98
	v_and_b32_e32 v106, 0xc0, v106
	v_sub_u32_e32 v102, 0, v106
	v_ashrrev_i32_e32 v103, 31, v102
	v_lshl_add_u64 v[102:103], v[102:103], 0, v[134:135]
	s_and_b64 s[24:25], s[82:83], exec
	s_cselect_b32 s14, 0, 15
	s_mul_i32 s8, s14, 0x110
	v_add_u32_e32 v99, s8, v98
	ds_read_b32 v64, v99 offset:0
	ds_read_b32 v65, v99 offset:64
	ds_read_b32 v66, v99 offset:128
	ds_read_b32 v67, v99 offset:192
	ds_read_b32 v76, v98 offset:9216
	ds_read_b32 v77, v98 offset:9280
	ds_read_b32 v78, v98 offset:9344
	ds_read_b32 v79, v98 offset:9408
	ds_read_b32 v88, v129 offset:9472
	s_waitcnt lgkmcnt(0)
	ds_read_b32 v68, v99 offset:11520
	ds_read_b32 v72, v99 offset:15872
	ds_read_b32 v80, v99 offset:4352
	ds_read_b32 v69, v99 offset:11584
	ds_read_b32 v73, v99 offset:15936
	ds_read_b32 v81, v99 offset:4416
	ds_read_b32 v70, v99 offset:11648
	ds_read_b32 v74, v99 offset:16000
	ds_read_b32 v82, v99 offset:4480
	ds_read_b32 v71, v99 offset:11712
	ds_read_b32 v75, v99 offset:16064
	ds_read_b32 v83, v99 offset:4544
	s_mov_b32 s4, 0
	s_mov_b32 s5, 15
	s_setprio 1
	s_cmp_lt_u32 s94, 0x14000
	s_cbranch_scc1 .Lprio_c_lo
	s_setprio 2
.Lprio_c_lo:
.Lscan_c_step:
	s_and_b64 s[24:25], s[82:83], exec
	s_cselect_b32 s14, s4, s5
	s_add_i32 s8, s14, s27
	s_max_i32 s8, s8, 0
	s_min_i32 s8, s8, 15
	s_mul_i32 s9, s8, 0x110
	v_add_u32_e32 v100, s9, v98
	s_mul_i32 s24, s8, 0x600
	s_ashr_i32 s25, s24, 31
	v_lshl_add_u64 v[104:105], v[102:103], 0, s[24:25]
	global_load_dword v84, v[104:105], off offset:768
	global_load_dword v85, v[104:105], off offset:832
	global_load_dword v86, v[104:105], off offset:896
	global_load_dword v87, v[104:105], off offset:960
	s_nop 0
	v_lshl_add_u64 v[104:105], v[134:135], 0, s[24:25]
	global_load_dword v89, v[104:105], off offset:1280
	s_waitcnt lgkmcnt(12)
	v_mul_f32_dpp v90, v64, v12 row_newbcast:0 row_mask:0xf bank_mask:0xf
	v_mul_f32_dpp v91, v64, v13 row_newbcast:1 row_mask:0xf bank_mask:0xf
	v_mul_f32_dpp v92, v64, v14 row_newbcast:2 row_mask:0xf bank_mask:0xf
	v_mul_f32_dpp v93, v64, v15 row_newbcast:3 row_mask:0xf bank_mask:0xf
	v_fmac_f32_dpp v90, v64, v8 row_newbcast:4 row_mask:0xf bank_mask:0xf
	v_fmac_f32_dpp v91, v64, v9 row_newbcast:5 row_mask:0xf bank_mask:0xf
	v_fmac_f32_dpp v92, v64, v10 row_newbcast:6 row_mask:0xf bank_mask:0xf
	v_fmac_f32_dpp v93, v64, v11 row_newbcast:7 row_mask:0xf bank_mask:0xf
	v_fmac_f32_dpp v90, v64, v4 row_newbcast:8 row_mask:0xf bank_mask:0xf
	v_fmac_f32_dpp v91, v64, v5 row_newbcast:9 row_mask:0xf bank_mask:0xf
	v_fmac_f32_dpp v92, v64, v6 row_newbcast:10 row_mask:0xf bank_mask:0xf
	v_fmac_f32_dpp v93, v64, v7 row_newbcast:11 row_mask:0xf bank_mask:0xf
	v_fmac_f32_dpp v90, v64, v0 row_newbcast:12 row_mask:0xf bank_mask:0xf
	v_fmac_f32_dpp v91, v64, v1 row_newbcast:13 row_mask:0xf bank_mask:0xf
	v_fmac_f32_dpp v92, v64, v2 row_newbcast:14 row_mask:0xf bank_mask:0xf
	v_fmac_f32_dpp v93, v64, v3 row_newbcast:15 row_mask:0xf bank_mask:0xf
	v_fmac_f32_dpp v90, v65, v28 row_newbcast:0 row_mask:0xf bank_mask:0xf
	v_fmac_f32_dpp v91, v65, v29 row_newbcast:1 row_mask:0xf bank_mask:0xf
	v_fmac_f32_dpp v92, v65, v30 row_newbcast:2 row_mask:0xf bank_mask:0xf
	v_fmac_f32_dpp v93, v65, v31 row_newbcast:3 row_mask:0xf bank_mask:0xf
	v_fmac_f32_dpp v90, v65, v24 row_newbcast:4 row_mask:0xf bank_mask:0xf
	v_fmac_f32_dpp v91, v65, v25 row_newbcast:5 row_mask:0xf bank_mask:0xf
	v_fmac_f32_dpp v92, v65, v26 row_newbcast:6 row_mask:0xf bank_mask:0xf
	v_fmac_f32_dpp v93, v65, v27 row_newbcast:7 row_mask:0xf bank_mask:0xf
	v_fmac_f32_dpp v90, v65, v20 row_newbcast:8 row_mask:0xf bank_mask:0xf
	v_fmac_f32_dpp v91, v65, v21 row_newbcast:9 row_mask:0xf bank_mask:0xf
	v_fmac_f32_dpp v92, v65, v22 row_newbcast:10 row_mask:0xf bank_mask:0xf
	v_fmac_f32_dpp v93, v65, v23 row_newbcast:11 row_mask:0xf bank_mask:0xf
	v_fmac_f32_dpp v90, v65, v16 row_newbcast:12 row_mask:0xf bank_mask:0xf
	v_fmac_f32_dpp v91, v65, v17 row_newbcast:13 row_mask:0xf bank_mask:0xf
	v_fmac_f32_dpp v92, v65, v18 row_newbcast:14 row_mask:0xf bank_mask:0xf
	v_fmac_f32_dpp v93, v65, v19 row_newbcast:15 row_mask:0xf bank_mask:0xf
	v_fmac_f32_dpp v90, v66, v44 row_newbcast:0 row_mask:0xf bank_mask:0xf
	v_fmac_f32_dpp v91, v66, v45 row_newbcast:1 row_mask:0xf bank_mask:0xf
	v_fmac_f32_dpp v92, v66, v46 row_newbcast:2 row_mask:0xf bank_mask:0xf
	v_fmac_f32_dpp v93, v66, v47 row_newbcast:3 row_mask:0xf bank_mask:0xf
	v_fmac_f32_dpp v90, v66, v40 row_newbcast:4 row_mask:0xf bank_mask:0xf
	v_fmac_f32_dpp v91, v66, v41 row_newbcast:5 row_mask:0xf bank_mask:0xf
	v_fmac_f32_dpp v92, v66, v42 row_newbcast:6 row_mask:0xf bank_mask:0xf
	v_fmac_f32_dpp v93, v66, v43 row_newbcast:7 row_mask:0xf bank_mask:0xf
	v_fmac_f32_dpp v90, v66, v36 row_newbcast:8 row_mask:0xf bank_mask:0xf
	v_fmac_f32_dpp v91, v66, v37 row_newbcast:9 row_mask:0xf bank_mask:0xf
	v_fmac_f32_dpp v92, v66, v38 row_newbcast:10 row_mask:0xf bank_mask:0xf
	v_fmac_f32_dpp v93, v66, v39 row_newbcast:11 row_mask:0xf bank_mask:0xf
	v_fmac_f32_dpp v90, v66, v32 row_newbcast:12 row_mask:0xf bank_mask:0xf
	v_fmac_f32_dpp v91, v66, v33 row_newbcast:13 row_mask:0xf bank_mask:0xf
	v_fmac_f32_dpp v92, v66, v34 row_newbcast:14 row_mask:0xf bank_mask:0xf
	v_fmac_f32_dpp v93, v66, v35 row_newbcast:15 row_mask:0xf bank_mask:0xf
	v_fmac_f32_dpp v90, v67, v60 row_newbcast:0 row_mask:0xf bank_mask:0xf
	v_fmac_f32_dpp v91, v67, v61 row_newbcast:1 row_mask:0xf bank_mask:0xf
	v_fmac_f32_dpp v92, v67, v62 row_newbcast:2 row_mask:0xf bank_mask:0xf
	v_fmac_f32_dpp v93, v67, v63 row_newbcast:3 row_mask:0xf bank_mask:0xf
	v_fmac_f32_dpp v90, v67, v56 row_newbcast:4 row_mask:0xf bank_mask:0xf
	v_fmac_f32_dpp v91, v67, v57 row_newbcast:5 row_mask:0xf bank_mask:0xf
	v_fmac_f32_dpp v92, v67, v58 row_newbcast:6 row_mask:0xf bank_mask:0xf
	v_fmac_f32_dpp v93, v67, v59 row_newbcast:7 row_mask:0xf bank_mask:0xf
	v_fmac_f32_dpp v90, v67, v52 row_newbcast:8 row_mask:0xf bank_mask:0xf
	v_fmac_f32_dpp v91, v67, v53 row_newbcast:9 row_mask:0xf bank_mask:0xf
	v_fmac_f32_dpp v92, v67, v54 row_newbcast:10 row_mask:0xf bank_mask:0xf
	v_fmac_f32_dpp v93, v67, v55 row_newbcast:11 row_mask:0xf bank_mask:0xf
	v_fmac_f32_dpp v90, v67, v48 row_newbcast:12 row_mask:0xf bank_mask:0xf
	v_fmac_f32_dpp v91, v67, v49 row_newbcast:13 row_mask:0xf bank_mask:0xf
	v_fmac_f32_dpp v92, v67, v50 row_newbcast:14 row_mask:0xf bank_mask:0xf
	v_fmac_f32_dpp v93, v67, v51 row_newbcast:15 row_mask:0xf bank_mask:0xf
	v_add_f32_e32 v90, v90, v91
	v_add_f32_e32 v92, v92, v93
	s_waitcnt lgkmcnt(0)
; template <int MODE>
; __device__ __forceinline__ void scan_item(const CAS Args* A, int l, int item, float* slab0, LAS float* ldsw, int lane) {
;     ...
;             const LAS f32x4* ua = (const LAS f32x4*)(ldsw + s * 64); const LAS f32x4* ur = (const LAS f32x4*)(ldsw + 1024 + s * 64); const LAS f32x4* uw = (const LAS f32x4*)(ldsw + 3072 + s * 64); const LAS f32x4* ub = (const LAS f32x4*)(ldsw + (MODE == 3 ? 1024 : 4096) + s * 64);
;             f2 sa2 = (f2){0.f, 0.f}, sb2 = (f2){0.f, 0.f}, pa2 = (f2){0.f, 0.f}, pb2 = (f2){0.f, 0.f};
; #pragma unroll
;             for (int j = 0; j < 16; ++j) { const f32x4 aq = ua[j]; const f2 a0 = (f2){aq.x, aq.y}, a1 = (f2){aq.z, aq.w}; sa2 = S[2 * j] * a0 + sa2; sb2 = S[2 * j + 1] * a1 + sb2;
;                 if (MODE == 3) { pa2 = Pm[2 * j] * a0 + pa2; pb2 = Pm[2 * j + 1] * a1 + pb2; } }
;             const float sa = (sa2.x + sa2.y) + (sb2.x + sb2.y), pa = (pa2.x + pa2.y) + (pb2.x + pb2.y); const f2 pas = (f2){pa, pa};
;             const f2 sas = (f2){sa, sa}, vvs = (f2){vv, vv};
;             f2 y2 = (f2){0.f, 0.f}, y3 = (f2){0.f, 0.f};
;             f32x4 nwq[2], nbq[2], nrq[2];
;             nwq[0] = uw[0]; nwq[1] = uw[1]; nbq[0] = ub[0]; nbq[1] = ub[1]; nrq[0] = (f32x4){0.f, 0.f, 0.f, 0.f}; nrq[1] = nrq[0];
;             if (MODE == 2) { nrq[0] = ur[0]; nrq[1] = ur[1]; }
; #pragma unroll
;             for (int g = 0; g < 8; ++g) {
;                 const f32x4 cwq0 = nwq[0], cwq1 = nwq[1], cbq0 = nbq[0], cbq1 = nbq[1], crq0 = nrq[0], crq1 = nrq[1];
;                 if (g < 7) { nwq[0] = uw[2 * g + 2]; nwq[1] = uw[2 * g + 3]; nbq[0] = ub[2 * g + 2]; nbq[1] = ub[2 * g + 3];
;                     if (MODE == 2) { nrq[0] = ur[2 * g + 2]; nrq[1] = ur[2 * g + 3]; } }
;                 f2 bb[4], ww[4], kq[4], rr[4];
;                 ww[0] = (f2){cwq0.x, cwq0.y}; ww[1] = (f2){cwq0.z, cwq0.w}; ww[2] = (f2){cwq1.x, cwq1.y}; ww[3] = (f2){cwq1.z, cwq1.w};
;                 bb[0] = (f2){cbq0.x, cbq0.y}; bb[1] = (f2){cbq0.z, cbq0.w}; bb[2] = (f2){cbq1.x, cbq1.y}; bb[3] = (f2){cbq1.z, cbq1.w};
;                 rr[0] = (f2){crq0.x, crq0.y}; rr[1] = (f2){crq0.z, crq0.w}; rr[2] = (f2){crq1.x, crq1.y}; rr[3] = (f2){crq1.z, crq1.w};
; #pragma unroll
;                 for (int q = 0; q < 4; ++q) { const int j = g * 4 + q; if (MODE != 1) kq[q] = RL2(ck, j); }
;                 __builtin_amdgcn_sched_barrier(0);
; #pragma unroll
	ds_read_b32 v64, v100 offset:0
	ds_read_b32 v65, v100 offset:64
	ds_read_b32 v66, v100 offset:128
	ds_read_b32 v67, v100 offset:192
	v_add_f32_e32 v90, v90, v92
	v_mul_f32_dpp v12, v68, v12 row_newbcast:0 row_mask:0xf bank_mask:0xf
	v_mul_f32_dpp v13, v68, v13 row_newbcast:1 row_mask:0xf bank_mask:0xf
	v_mul_f32_dpp v14, v68, v14 row_newbcast:2 row_mask:0xf bank_mask:0xf
	v_mul_f32_dpp v15, v68, v15 row_newbcast:3 row_mask:0xf bank_mask:0xf
	v_fmac_f32_dpp v12, v72, v90 row_newbcast:0 row_mask:0xf bank_mask:0xf
	v_fmac_f32_dpp v13, v72, v90 row_newbcast:1 row_mask:0xf bank_mask:0xf
	v_fmac_f32_dpp v14, v72, v90 row_newbcast:2 row_mask:0xf bank_mask:0xf
	v_fmac_f32_dpp v15, v72, v90 row_newbcast:3 row_mask:0xf bank_mask:0xf
	v_fmac_f32_dpp v12, v76, v88 row_newbcast:0 row_mask:0xf bank_mask:0xf
	v_fmac_f32_dpp v13, v76, v88 row_newbcast:1 row_mask:0xf bank_mask:0xf
	v_fmac_f32_dpp v14, v76, v88 row_newbcast:2 row_mask:0xf bank_mask:0xf
	v_fmac_f32_dpp v15, v76, v88 row_newbcast:3 row_mask:0xf bank_mask:0xf
	v_mul_f32_dpp v94, v80, v12 row_newbcast:0 row_mask:0xf bank_mask:0xf
	v_mul_f32_dpp v95, v80, v13 row_newbcast:1 row_mask:0xf bank_mask:0xf
	v_mul_f32_dpp v96, v80, v14 row_newbcast:2 row_mask:0xf bank_mask:0xf
	v_mul_f32_dpp v97, v80, v15 row_newbcast:3 row_mask:0xf bank_mask:0xf
	v_mul_f32_dpp v8, v68, v8 row_newbcast:4 row_mask:0xf bank_mask:0xf
	v_mul_f32_dpp v9, v68, v9 row_newbcast:5 row_mask:0xf bank_mask:0xf
	v_mul_f32_dpp v10, v68, v10 row_newbcast:6 row_mask:0xf bank_mask:0xf
	v_mul_f32_dpp v11, v68, v11 row_newbcast:7 row_mask:0xf bank_mask:0xf
	v_fmac_f32_dpp v8, v72, v90 row_newbcast:4 row_mask:0xf bank_mask:0xf
	v_fmac_f32_dpp v9, v72, v90 row_newbcast:5 row_mask:0xf bank_mask:0xf
	v_fmac_f32_dpp v10, v72, v90 row_newbcast:6 row_mask:0xf bank_mask:0xf
	v_fmac_f32_dpp v11, v72, v90 row_newbcast:7 row_mask:0xf bank_mask:0xf
	v_fmac_f32_dpp v8, v76, v88 row_newbcast:4 row_mask:0xf bank_mask:0xf
	v_fmac_f32_dpp v9, v76, v88 row_newbcast:5 row_mask:0xf bank_mask:0xf
	v_fmac_f32_dpp v10, v76, v88 row_newbcast:6 row_mask:0xf bank_mask:0xf
	v_fmac_f32_dpp v11, v76, v88 row_newbcast:7 row_mask:0xf bank_mask:0xf
	v_fmac_f32_dpp v94, v80, v8 row_newbcast:4 row_mask:0xf bank_mask:0xf
	v_fmac_f32_dpp v95, v80, v9 row_newbcast:5 row_mask:0xf bank_mask:0xf
	v_fmac_f32_dpp v96, v80, v10 row_newbcast:6 row_mask:0xf bank_mask:0xf
	v_fmac_f32_dpp v97, v80, v11 row_newbcast:7 row_mask:0xf bank_mask:0xf
	v_mul_f32_dpp v4, v68, v4 row_newbcast:8 row_mask:0xf bank_mask:0xf
	v_mul_f32_dpp v5, v68, v5 row_newbcast:9 row_mask:0xf bank_mask:0xf
	v_mul_f32_dpp v6, v68, v6 row_newbcast:10 row_mask:0xf bank_mask:0xf
	v_mul_f32_dpp v7, v68, v7 row_newbcast:11 row_mask:0xf bank_mask:0xf
	v_fmac_f32_dpp v4, v72, v90 row_newbcast:8 row_mask:0xf bank_mask:0xf
	v_fmac_f32_dpp v5, v72, v90 row_newbcast:9 row_mask:0xf bank_mask:0xf
	v_fmac_f32_dpp v6, v72, v90 row_newbcast:10 row_mask:0xf bank_mask:0xf
	v_fmac_f32_dpp v7, v72, v90 row_newbcast:11 row_mask:0xf bank_mask:0xf
	v_fmac_f32_dpp v4, v76, v88 row_newbcast:8 row_mask:0xf bank_mask:0xf
	v_fmac_f32_dpp v5, v76, v88 row_newbcast:9 row_mask:0xf bank_mask:0xf
	v_fmac_f32_dpp v6, v76, v88 row_newbcast:10 row_mask:0xf bank_mask:0xf
	v_fmac_f32_dpp v7, v76, v88 row_newbcast:11 row_mask:0xf bank_mask:0xf
	v_fmac_f32_dpp v94, v80, v4 row_newbcast:8 row_mask:0xf bank_mask:0xf
	v_fmac_f32_dpp v95, v80, v5 row_newbcast:9 row_mask:0xf bank_mask:0xf
	v_fmac_f32_dpp v96, v80, v6 row_newbcast:10 row_mask:0xf bank_mask:0xf
	v_fmac_f32_dpp v97, v80, v7 row_newbcast:11 row_mask:0xf bank_mask:0xf
	v_mul_f32_dpp v0, v68, v0 row_newbcast:12 row_mask:0xf bank_mask:0xf
	v_mul_f32_dpp v1, v68, v1 row_newbcast:13 row_mask:0xf bank_mask:0xf
	v_mul_f32_dpp v2, v68, v2 row_newbcast:14 row_mask:0xf bank_mask:0xf
	v_mul_f32_dpp v3, v68, v3 row_newbcast:15 row_mask:0xf bank_mask:0xf
	v_fmac_f32_dpp v0, v72, v90 row_newbcast:12 row_mask:0xf bank_mask:0xf
	v_fmac_f32_dpp v1, v72, v90 row_newbcast:13 row_mask:0xf bank_mask:0xf
	v_fmac_f32_dpp v2, v72, v90 row_newbcast:14 row_mask:0xf bank_mask:0xf
	v_fmac_f32_dpp v3, v72, v90 row_newbcast:15 row_mask:0xf bank_mask:0xf
	v_fmac_f32_dpp v0, v76, v88 row_newbcast:12 row_mask:0xf bank_mask:0xf
	v_fmac_f32_dpp v1, v76, v88 row_newbcast:13 row_mask:0xf bank_mask:0xf
	v_fmac_f32_dpp v2, v76, v88 row_newbcast:14 row_mask:0xf bank_mask:0xf
	v_fmac_f32_dpp v3, v76, v88 row_newbcast:15 row_mask:0xf bank_mask:0xf
	v_fmac_f32_dpp v94, v80, v0 row_newbcast:12 row_mask:0xf bank_mask:0xf
	v_fmac_f32_dpp v95, v80, v1 row_newbcast:13 row_mask:0xf bank_mask:0xf
	v_fmac_f32_dpp v96, v80, v2 row_newbcast:14 row_mask:0xf bank_mask:0xf
	v_fmac_f32_dpp v97, v80, v3 row_newbcast:15 row_mask:0xf bank_mask:0xf
	ds_read_b32 v68, v100 offset:11520
	ds_read_b32 v72, v100 offset:15872
	ds_read_b32 v80, v100 offset:4352
	v_mul_f32_dpp v28, v69, v28 row_newbcast:0 row_mask:0xf bank_mask:0xf
	v_mul_f32_dpp v29, v69, v29 row_newbcast:1 row_mask:0xf bank_mask:0xf
	v_mul_f32_dpp v30, v69, v30 row_newbcast:2 row_mask:0xf bank_mask:0xf
	v_mul_f32_dpp v31, v69, v31 row_newbcast:3 row_mask:0xf bank_mask:0xf
	v_fmac_f32_dpp v28, v73, v90 row_newbcast:0 row_mask:0xf bank_mask:0xf
	v_fmac_f32_dpp v29, v73, v90 row_newbcast:1 row_mask:0xf bank_mask:0xf
	v_fmac_f32_dpp v30, v73, v90 row_newbcast:2 row_mask:0xf bank_mask:0xf
	v_fmac_f32_dpp v31, v73, v90 row_newbcast:3 row_mask:0xf bank_mask:0xf
	v_fmac_f32_dpp v28, v77, v88 row_newbcast:0 row_mask:0xf bank_mask:0xf
	v_fmac_f32_dpp v29, v77, v88 row_newbcast:1 row_mask:0xf bank_mask:0xf
	v_fmac_f32_dpp v30, v77, v88 row_newbcast:2 row_mask:0xf bank_mask:0xf
; #define RL2(x, j) (f2){__builtin_bit_cast(float, __builtin_amdgcn_readlane(__builtin_bit_cast(int, x), 2 * (j))), __builtin_bit_cast(float, __builtin_amdgcn_readlane(__builtin_bit_cast(int, x), 2 * (j) + 1))}
; template <int MODE>
; __device__ __forceinline__ void scan_item(const CAS Args* A, int l, int item, float* slab0, LAS float* ldsw, int lane) {
;     ...
;             for (int g = 0; g < 8; ++g) {
;                 const f32x4 cwq0 = nwq[0], cwq1 = nwq[1], cbq0 = nbq[0], cbq1 = nbq[1], crq0 = nrq[0], crq1 = nrq[1];
;                 if (g < 7) { nwq[0] = uw[2 * g + 2]; nwq[1] = uw[2 * g + 3]; nbq[0] = ub[2 * g + 2]; nbq[1] = ub[2 * g + 3];
;                     if (MODE == 2) { nrq[0] = ur[2 * g + 2]; nrq[1] = ur[2 * g + 3]; } }
;                 f2 bb[4], ww[4], kq[4], rr[4];
;                 ww[0] = (f2){cwq0.x, cwq0.y}; ww[1] = (f2){cwq0.z, cwq0.w}; ww[2] = (f2){cwq1.x, cwq1.y}; ww[3] = (f2){cwq1.z, cwq1.w};
;                 bb[0] = (f2){cbq0.x, cbq0.y}; bb[1] = (f2){cbq0.z, cbq0.w}; bb[2] = (f2){cbq1.x, cbq1.y}; bb[3] = (f2){cbq1.z, cbq1.w};
;                 rr[0] = (f2){crq0.x, crq0.y}; rr[1] = (f2){crq0.z, crq0.w}; rr[2] = (f2){crq1.x, crq1.y}; rr[3] = (f2){crq1.z, crq1.w};
; #pragma unroll
;                 for (int q = 0; q < 4; ++q) { const int j = g * 4 + q; if (MODE != 1) kq[q] = RL2(ck, j); }
;                 __builtin_amdgcn_sched_barrier(0);
; #pragma unroll
;                 for (int q = 0; q < 4; ++q) { const int j = g * 4 + q;
;                     f2 t = sas * bb[q];
;                     if (MODE != 1) t = vvs * kq[q] + t;
;                     S[j] = S[j] * ww[q] + t;
;                     if (MODE == 3) Pm[j] = Pm[j] * ww[q] + pas * bb[q];
;                     if (MODE == 2) { if (j & 1) y3 = S[j] * rr[q] + y3; else y2 = S[j] * rr[q] + y2; } }
	v_fmac_f32_dpp v31, v77, v88 row_newbcast:3 row_mask:0xf bank_mask:0xf
	v_fmac_f32_dpp v94, v81, v28 row_newbcast:0 row_mask:0xf bank_mask:0xf
	v_fmac_f32_dpp v95, v81, v29 row_newbcast:1 row_mask:0xf bank_mask:0xf
	v_fmac_f32_dpp v96, v81, v30 row_newbcast:2 row_mask:0xf bank_mask:0xf
	v_fmac_f32_dpp v97, v81, v31 row_newbcast:3 row_mask:0xf bank_mask:0xf
	v_mul_f32_dpp v24, v69, v24 row_newbcast:4 row_mask:0xf bank_mask:0xf
	v_mul_f32_dpp v25, v69, v25 row_newbcast:5 row_mask:0xf bank_mask:0xf
	v_mul_f32_dpp v26, v69, v26 row_newbcast:6 row_mask:0xf bank_mask:0xf
	v_mul_f32_dpp v27, v69, v27 row_newbcast:7 row_mask:0xf bank_mask:0xf
	v_fmac_f32_dpp v24, v73, v90 row_newbcast:4 row_mask:0xf bank_mask:0xf
	v_fmac_f32_dpp v25, v73, v90 row_newbcast:5 row_mask:0xf bank_mask:0xf
	v_fmac_f32_dpp v26, v73, v90 row_newbcast:6 row_mask:0xf bank_mask:0xf
	v_fmac_f32_dpp v27, v73, v90 row_newbcast:7 row_mask:0xf bank_mask:0xf
	v_fmac_f32_dpp v24, v77, v88 row_newbcast:4 row_mask:0xf bank_mask:0xf
	v_fmac_f32_dpp v25, v77, v88 row_newbcast:5 row_mask:0xf bank_mask:0xf
	v_fmac_f32_dpp v26, v77, v88 row_newbcast:6 row_mask:0xf bank_mask:0xf
	v_fmac_f32_dpp v27, v77, v88 row_newbcast:7 row_mask:0xf bank_mask:0xf
	v_fmac_f32_dpp v94, v81, v24 row_newbcast:4 row_mask:0xf bank_mask:0xf
	v_fmac_f32_dpp v95, v81, v25 row_newbcast:5 row_mask:0xf bank_mask:0xf
	v_fmac_f32_dpp v96, v81, v26 row_newbcast:6 row_mask:0xf bank_mask:0xf
	v_fmac_f32_dpp v97, v81, v27 row_newbcast:7 row_mask:0xf bank_mask:0xf
	v_mul_f32_dpp v20, v69, v20 row_newbcast:8 row_mask:0xf bank_mask:0xf
	v_mul_f32_dpp v21, v69, v21 row_newbcast:9 row_mask:0xf bank_mask:0xf
	v_mul_f32_dpp v22, v69, v22 row_newbcast:10 row_mask:0xf bank_mask:0xf
	v_mul_f32_dpp v23, v69, v23 row_newbcast:11 row_mask:0xf bank_mask:0xf
	v_fmac_f32_dpp v20, v73, v90 row_newbcast:8 row_mask:0xf bank_mask:0xf
	v_fmac_f32_dpp v21, v73, v90 row_newbcast:9 row_mask:0xf bank_mask:0xf
	v_fmac_f32_dpp v22, v73, v90 row_newbcast:10 row_mask:0xf bank_mask:0xf
	v_fmac_f32_dpp v23, v73, v90 row_newbcast:11 row_mask:0xf bank_mask:0xf
	v_fmac_f32_dpp v20, v77, v88 row_newbcast:8 row_mask:0xf bank_mask:0xf
	v_fmac_f32_dpp v21, v77, v88 row_newbcast:9 row_mask:0xf bank_mask:0xf
	v_fmac_f32_dpp v22, v77, v88 row_newbcast:10 row_mask:0xf bank_mask:0xf
	v_fmac_f32_dpp v23, v77, v88 row_newbcast:11 row_mask:0xf bank_mask:0xf
	v_fmac_f32_dpp v94, v81, v20 row_newbcast:8 row_mask:0xf bank_mask:0xf
	v_fmac_f32_dpp v95, v81, v21 row_newbcast:9 row_mask:0xf bank_mask:0xf
	v_fmac_f32_dpp v96, v81, v22 row_newbcast:10 row_mask:0xf bank_mask:0xf
	v_fmac_f32_dpp v97, v81, v23 row_newbcast:11 row_mask:0xf bank_mask:0xf
	v_mul_f32_dpp v16, v69, v16 row_newbcast:12 row_mask:0xf bank_mask:0xf
	v_mul_f32_dpp v17, v69, v17 row_newbcast:13 row_mask:0xf bank_mask:0xf
	v_mul_f32_dpp v18, v69, v18 row_newbcast:14 row_mask:0xf bank_mask:0xf
	v_mul_f32_dpp v19, v69, v19 row_newbcast:15 row_mask:0xf bank_mask:0xf
	v_fmac_f32_dpp v16, v73, v90 row_newbcast:12 row_mask:0xf bank_mask:0xf
	v_fmac_f32_dpp v17, v73, v90 row_newbcast:13 row_mask:0xf bank_mask:0xf
	v_fmac_f32_dpp v18, v73, v90 row_newbcast:14 row_mask:0xf bank_mask:0xf
	v_fmac_f32_dpp v19, v73, v90 row_newbcast:15 row_mask:0xf bank_mask:0xf
	v_fmac_f32_dpp v16, v77, v88 row_newbcast:12 row_mask:0xf bank_mask:0xf
	v_fmac_f32_dpp v17, v77, v88 row_newbcast:13 row_mask:0xf bank_mask:0xf
	v_fmac_f32_dpp v18, v77, v88 row_newbcast:14 row_mask:0xf bank_mask:0xf
	v_fmac_f32_dpp v19, v77, v88 row_newbcast:15 row_mask:0xf bank_mask:0xf
	v_fmac_f32_dpp v94, v81, v16 row_newbcast:12 row_mask:0xf bank_mask:0xf
	v_fmac_f32_dpp v95, v81, v17 row_newbcast:13 row_mask:0xf bank_mask:0xf
	v_fmac_f32_dpp v96, v81, v18 row_newbcast:14 row_mask:0xf bank_mask:0xf
	v_fmac_f32_dpp v97, v81, v19 row_newbcast:15 row_mask:0xf bank_mask:0xf
	ds_read_b32 v69, v100 offset:11584
	ds_read_b32 v73, v100 offset:15936
	ds_read_b32 v81, v100 offset:4416
	v_mul_f32_dpp v44, v70, v44 row_newbcast:0 row_mask:0xf bank_mask:0xf
	v_mul_f32_dpp v45, v70, v45 row_newbcast:1 row_mask:0xf bank_mask:0xf
	v_mul_f32_dpp v46, v70, v46 row_newbcast:2 row_mask:0xf bank_mask:0xf
	v_mul_f32_dpp v47, v70, v47 row_newbcast:3 row_mask:0xf bank_mask:0xf
	v_fmac_f32_dpp v44, v74, v90 row_newbcast:0 row_mask:0xf bank_mask:0xf
	v_fmac_f32_dpp v45, v74, v90 row_newbcast:1 row_mask:0xf bank_mask:0xf
	v_fmac_f32_dpp v46, v74, v90 row_newbcast:2 row_mask:0xf bank_mask:0xf
	v_fmac_f32_dpp v47, v74, v90 row_newbcast:3 row_mask:0xf bank_mask:0xf
	v_fmac_f32_dpp v44, v78, v88 row_newbcast:0 row_mask:0xf bank_mask:0xf
	v_fmac_f32_dpp v45, v78, v88 row_newbcast:1 row_mask:0xf bank_mask:0xf
	v_fmac_f32_dpp v46, v78, v88 row_newbcast:2 row_mask:0xf bank_mask:0xf
	v_fmac_f32_dpp v47, v78, v88 row_newbcast:3 row_mask:0xf bank_mask:0xf
	v_fmac_f32_dpp v94, v82, v44 row_newbcast:0 row_mask:0xf bank_mask:0xf
	v_fmac_f32_dpp v95, v82, v45 row_newbcast:1 row_mask:0xf bank_mask:0xf
	v_fmac_f32_dpp v96, v82, v46 row_newbcast:2 row_mask:0xf bank_mask:0xf
	v_fmac_f32_dpp v97, v82, v47 row_newbcast:3 row_mask:0xf bank_mask:0xf
	v_mul_f32_dpp v40, v70, v40 row_newbcast:4 row_mask:0xf bank_mask:0xf
	v_mul_f32_dpp v41, v70, v41 row_newbcast:5 row_mask:0xf bank_mask:0xf
	v_mul_f32_dpp v42, v70, v42 row_newbcast:6 row_mask:0xf bank_mask:0xf
	v_mul_f32_dpp v43, v70, v43 row_newbcast:7 row_mask:0xf bank_mask:0xf
	v_fmac_f32_dpp v40, v74, v90 row_newbcast:4 row_mask:0xf bank_mask:0xf
	v_fmac_f32_dpp v41, v74, v90 row_newbcast:5 row_mask:0xf bank_mask:0xf
	v_fmac_f32_dpp v42, v74, v90 row_newbcast:6 row_mask:0xf bank_mask:0xf
	v_fmac_f32_dpp v43, v74, v90 row_newbcast:7 row_mask:0xf bank_mask:0xf
; #define RL2(x, j) (f2){__builtin_bit_cast(float, __builtin_amdgcn_readlane(__builtin_bit_cast(int, x), 2 * (j))), __builtin_bit_cast(float, __builtin_amdgcn_readlane(__builtin_bit_cast(int, x), 2 * (j) + 1))}
; template <int MODE>
; __device__ __forceinline__ void scan_item(const CAS Args* A, int l, int item, float* slab0, LAS float* ldsw, int lane) {
;     ...
;             for (int g = 0; g < 8; ++g) {
;                 const f32x4 cwq0 = nwq[0], cwq1 = nwq[1], cbq0 = nbq[0], cbq1 = nbq[1], crq0 = nrq[0], crq1 = nrq[1];
;                 if (g < 7) { nwq[0] = uw[2 * g + 2]; nwq[1] = uw[2 * g + 3]; nbq[0] = ub[2 * g + 2]; nbq[1] = ub[2 * g + 3];
;                     if (MODE == 2) { nrq[0] = ur[2 * g + 2]; nrq[1] = ur[2 * g + 3]; } }
;                 f2 bb[4], ww[4], kq[4], rr[4];
;                 ww[0] = (f2){cwq0.x, cwq0.y}; ww[1] = (f2){cwq0.z, cwq0.w}; ww[2] = (f2){cwq1.x, cwq1.y}; ww[3] = (f2){cwq1.z, cwq1.w};
;                 bb[0] = (f2){cbq0.x, cbq0.y}; bb[1] = (f2){cbq0.z, cbq0.w}; bb[2] = (f2){cbq1.x, cbq1.y}; bb[3] = (f2){cbq1.z, cbq1.w};
;                 rr[0] = (f2){crq0.x, crq0.y}; rr[1] = (f2){crq0.z, crq0.w}; rr[2] = (f2){crq1.x, crq1.y}; rr[3] = (f2){crq1.z, crq1.w};
; #pragma unroll
;                 for (int q = 0; q < 4; ++q) { const int j = g * 4 + q; if (MODE != 1) kq[q] = RL2(ck, j); }
;                 __builtin_amdgcn_sched_barrier(0);
; #pragma unroll
;                 for (int q = 0; q < 4; ++q) { const int j = g * 4 + q;
;                     f2 t = sas * bb[q];
;                     if (MODE != 1) t = vvs * kq[q] + t;
;                     S[j] = S[j] * ww[q] + t;
;                     if (MODE == 3) Pm[j] = Pm[j] * ww[q] + pas * bb[q];
;                     if (MODE == 2) { if (j & 1) y3 = S[j] * rr[q] + y3; else y2 = S[j] * rr[q] + y2; } }
	v_fmac_f32_dpp v40, v78, v88 row_newbcast:4 row_mask:0xf bank_mask:0xf
	v_fmac_f32_dpp v41, v78, v88 row_newbcast:5 row_mask:0xf bank_mask:0xf
	v_fmac_f32_dpp v42, v78, v88 row_newbcast:6 row_mask:0xf bank_mask:0xf
	v_fmac_f32_dpp v43, v78, v88 row_newbcast:7 row_mask:0xf bank_mask:0xf
	v_fmac_f32_dpp v94, v82, v40 row_newbcast:4 row_mask:0xf bank_mask:0xf
	v_fmac_f32_dpp v95, v82, v41 row_newbcast:5 row_mask:0xf bank_mask:0xf
	v_fmac_f32_dpp v96, v82, v42 row_newbcast:6 row_mask:0xf bank_mask:0xf
	v_fmac_f32_dpp v97, v82, v43 row_newbcast:7 row_mask:0xf bank_mask:0xf
	v_mul_f32_dpp v36, v70, v36 row_newbcast:8 row_mask:0xf bank_mask:0xf
	v_mul_f32_dpp v37, v70, v37 row_newbcast:9 row_mask:0xf bank_mask:0xf
	v_mul_f32_dpp v38, v70, v38 row_newbcast:10 row_mask:0xf bank_mask:0xf
	v_mul_f32_dpp v39, v70, v39 row_newbcast:11 row_mask:0xf bank_mask:0xf
	v_fmac_f32_dpp v36, v74, v90 row_newbcast:8 row_mask:0xf bank_mask:0xf
	v_fmac_f32_dpp v37, v74, v90 row_newbcast:9 row_mask:0xf bank_mask:0xf
	v_fmac_f32_dpp v38, v74, v90 row_newbcast:10 row_mask:0xf bank_mask:0xf
	v_fmac_f32_dpp v39, v74, v90 row_newbcast:11 row_mask:0xf bank_mask:0xf
	v_fmac_f32_dpp v36, v78, v88 row_newbcast:8 row_mask:0xf bank_mask:0xf
	v_fmac_f32_dpp v37, v78, v88 row_newbcast:9 row_mask:0xf bank_mask:0xf
	v_fmac_f32_dpp v38, v78, v88 row_newbcast:10 row_mask:0xf bank_mask:0xf
	v_fmac_f32_dpp v39, v78, v88 row_newbcast:11 row_mask:0xf bank_mask:0xf
	v_fmac_f32_dpp v94, v82, v36 row_newbcast:8 row_mask:0xf bank_mask:0xf
	v_fmac_f32_dpp v95, v82, v37 row_newbcast:9 row_mask:0xf bank_mask:0xf
	v_fmac_f32_dpp v96, v82, v38 row_newbcast:10 row_mask:0xf bank_mask:0xf
	v_fmac_f32_dpp v97, v82, v39 row_newbcast:11 row_mask:0xf bank_mask:0xf
	v_mul_f32_dpp v32, v70, v32 row_newbcast:12 row_mask:0xf bank_mask:0xf
	v_mul_f32_dpp v33, v70, v33 row_newbcast:13 row_mask:0xf bank_mask:0xf
	v_mul_f32_dpp v34, v70, v34 row_newbcast:14 row_mask:0xf bank_mask:0xf
	v_mul_f32_dpp v35, v70, v35 row_newbcast:15 row_mask:0xf bank_mask:0xf
	v_fmac_f32_dpp v32, v74, v90 row_newbcast:12 row_mask:0xf bank_mask:0xf
	v_fmac_f32_dpp v33, v74, v90 row_newbcast:13 row_mask:0xf bank_mask:0xf
	v_fmac_f32_dpp v34, v74, v90 row_newbcast:14 row_mask:0xf bank_mask:0xf
	v_fmac_f32_dpp v35, v74, v90 row_newbcast:15 row_mask:0xf bank_mask:0xf
	v_fmac_f32_dpp v32, v78, v88 row_newbcast:12 row_mask:0xf bank_mask:0xf
	v_fmac_f32_dpp v33, v78, v88 row_newbcast:13 row_mask:0xf bank_mask:0xf
	v_fmac_f32_dpp v34, v78, v88 row_newbcast:14 row_mask:0xf bank_mask:0xf
	v_fmac_f32_dpp v35, v78, v88 row_newbcast:15 row_mask:0xf bank_mask:0xf
	v_fmac_f32_dpp v94, v82, v32 row_newbcast:12 row_mask:0xf bank_mask:0xf
	v_fmac_f32_dpp v95, v82, v33 row_newbcast:13 row_mask:0xf bank_mask:0xf
	v_fmac_f32_dpp v96, v82, v34 row_newbcast:14 row_mask:0xf bank_mask:0xf
	v_fmac_f32_dpp v97, v82, v35 row_newbcast:15 row_mask:0xf bank_mask:0xf
	ds_read_b32 v70, v100 offset:11648
	ds_read_b32 v74, v100 offset:16000
	ds_read_b32 v82, v100 offset:4480
	v_mul_f32_dpp v60, v71, v60 row_newbcast:0 row_mask:0xf bank_mask:0xf
	v_mul_f32_dpp v61, v71, v61 row_newbcast:1 row_mask:0xf bank_mask:0xf
	v_mul_f32_dpp v62, v71, v62 row_newbcast:2 row_mask:0xf bank_mask:0xf
	v_mul_f32_dpp v63, v71, v63 row_newbcast:3 row_mask:0xf bank_mask:0xf
	v_fmac_f32_dpp v60, v75, v90 row_newbcast:0 row_mask:0xf bank_mask:0xf
	v_fmac_f32_dpp v61, v75, v90 row_newbcast:1 row_mask:0xf bank_mask:0xf
	v_fmac_f32_dpp v62, v75, v90 row_newbcast:2 row_mask:0xf bank_mask:0xf
	v_fmac_f32_dpp v63, v75, v90 row_newbcast:3 row_mask:0xf bank_mask:0xf
	v_fmac_f32_dpp v60, v79, v88 row_newbcast:0 row_mask:0xf bank_mask:0xf
	v_fmac_f32_dpp v61, v79, v88 row_newbcast:1 row_mask:0xf bank_mask:0xf
	v_fmac_f32_dpp v62, v79, v88 row_newbcast:2 row_mask:0xf bank_mask:0xf
	v_fmac_f32_dpp v63, v79, v88 row_newbcast:3 row_mask:0xf bank_mask:0xf
	v_fmac_f32_dpp v94, v83, v60 row_newbcast:0 row_mask:0xf bank_mask:0xf
	v_fmac_f32_dpp v95, v83, v61 row_newbcast:1 row_mask:0xf bank_mask:0xf
	v_fmac_f32_dpp v96, v83, v62 row_newbcast:2 row_mask:0xf bank_mask:0xf
	v_fmac_f32_dpp v97, v83, v63 row_newbcast:3 row_mask:0xf bank_mask:0xf
; __device__ __forceinline__ unsigned f2bf(float f) { return pk2(f, f) & 0xffffu; }
; #define RL2(x, j) (f2){__builtin_bit_cast(float, __builtin_amdgcn_readlane(__builtin_bit_cast(int, x), 2 * (j))), __builtin_bit_cast(float, __builtin_amdgcn_readlane(__builtin_bit_cast(int, x), 2 * (j) + 1))}
; #define lane LANE_()
; template <int MODE>
; __device__ __forceinline__ void scan_item(const CAS Args* A, int l, int item, float* slab0, LAS float* ldsw, int lane) {
;     ...
;             for (int g = 0; g < 8; ++g) {
;                 const f32x4 cwq0 = nwq[0], cwq1 = nwq[1], cbq0 = nbq[0], cbq1 = nbq[1], crq0 = nrq[0], crq1 = nrq[1];
;                 if (g < 7) { nwq[0] = uw[2 * g + 2]; nwq[1] = uw[2 * g + 3]; nbq[0] = ub[2 * g + 2]; nbq[1] = ub[2 * g + 3];
;                     if (MODE == 2) { nrq[0] = ur[2 * g + 2]; nrq[1] = ur[2 * g + 3]; } }
;                 f2 bb[4], ww[4], kq[4], rr[4];
;                 ww[0] = (f2){cwq0.x, cwq0.y}; ww[1] = (f2){cwq0.z, cwq0.w}; ww[2] = (f2){cwq1.x, cwq1.y}; ww[3] = (f2){cwq1.z, cwq1.w};
;                 bb[0] = (f2){cbq0.x, cbq0.y}; bb[1] = (f2){cbq0.z, cbq0.w}; bb[2] = (f2){cbq1.x, cbq1.y}; bb[3] = (f2){cbq1.z, cbq1.w};
;                 rr[0] = (f2){crq0.x, crq0.y}; rr[1] = (f2){crq0.z, crq0.w}; rr[2] = (f2){crq1.x, crq1.y}; rr[3] = (f2){crq1.z, crq1.w};
; #pragma unroll
;                 for (int q = 0; q < 4; ++q) { const int j = g * 4 + q; if (MODE != 1) kq[q] = RL2(ck, j); }
;                 __builtin_amdgcn_sched_barrier(0);
; #pragma unroll
;                 for (int q = 0; q < 4; ++q) { const int j = g * 4 + q;
;                     f2 t = sas * bb[q];
;                     if (MODE != 1) t = vvs * kq[q] + t;
;                     S[j] = S[j] * ww[q] + t;
;                     if (MODE == 3) Pm[j] = Pm[j] * ww[q] + pas * bb[q];
;                     if (MODE == 2) { if (j & 1) y3 = S[j] * rr[q] + y3; else y2 = S[j] * rr[q] + y2; } }
;             }
;             if (MODE == 2) yb[(size_t)(t0 + s) * 512 + h * 64 + lane] = (bf16)f2bf((y2.x + y2.y) + (y3.x + y3.y));
;         }
	v_mul_f32_dpp v56, v71, v56 row_newbcast:4 row_mask:0xf bank_mask:0xf
	v_mul_f32_dpp v57, v71, v57 row_newbcast:5 row_mask:0xf bank_mask:0xf
	v_mul_f32_dpp v58, v71, v58 row_newbcast:6 row_mask:0xf bank_mask:0xf
	v_mul_f32_dpp v59, v71, v59 row_newbcast:7 row_mask:0xf bank_mask:0xf
	v_fmac_f32_dpp v56, v75, v90 row_newbcast:4 row_mask:0xf bank_mask:0xf
	v_fmac_f32_dpp v57, v75, v90 row_newbcast:5 row_mask:0xf bank_mask:0xf
	v_fmac_f32_dpp v58, v75, v90 row_newbcast:6 row_mask:0xf bank_mask:0xf
	v_fmac_f32_dpp v59, v75, v90 row_newbcast:7 row_mask:0xf bank_mask:0xf
	v_fmac_f32_dpp v56, v79, v88 row_newbcast:4 row_mask:0xf bank_mask:0xf
	v_fmac_f32_dpp v57, v79, v88 row_newbcast:5 row_mask:0xf bank_mask:0xf
	v_fmac_f32_dpp v58, v79, v88 row_newbcast:6 row_mask:0xf bank_mask:0xf
	v_fmac_f32_dpp v59, v79, v88 row_newbcast:7 row_mask:0xf bank_mask:0xf
	v_fmac_f32_dpp v94, v83, v56 row_newbcast:4 row_mask:0xf bank_mask:0xf
	v_fmac_f32_dpp v95, v83, v57 row_newbcast:5 row_mask:0xf bank_mask:0xf
	v_fmac_f32_dpp v96, v83, v58 row_newbcast:6 row_mask:0xf bank_mask:0xf
	v_fmac_f32_dpp v97, v83, v59 row_newbcast:7 row_mask:0xf bank_mask:0xf
	v_mul_f32_dpp v52, v71, v52 row_newbcast:8 row_mask:0xf bank_mask:0xf
	v_mul_f32_dpp v53, v71, v53 row_newbcast:9 row_mask:0xf bank_mask:0xf
	v_mul_f32_dpp v54, v71, v54 row_newbcast:10 row_mask:0xf bank_mask:0xf
	v_mul_f32_dpp v55, v71, v55 row_newbcast:11 row_mask:0xf bank_mask:0xf
	v_fmac_f32_dpp v52, v75, v90 row_newbcast:8 row_mask:0xf bank_mask:0xf
	v_fmac_f32_dpp v53, v75, v90 row_newbcast:9 row_mask:0xf bank_mask:0xf
	v_fmac_f32_dpp v54, v75, v90 row_newbcast:10 row_mask:0xf bank_mask:0xf
	v_fmac_f32_dpp v55, v75, v90 row_newbcast:11 row_mask:0xf bank_mask:0xf
	v_fmac_f32_dpp v52, v79, v88 row_newbcast:8 row_mask:0xf bank_mask:0xf
	v_fmac_f32_dpp v53, v79, v88 row_newbcast:9 row_mask:0xf bank_mask:0xf
	v_fmac_f32_dpp v54, v79, v88 row_newbcast:10 row_mask:0xf bank_mask:0xf
	v_fmac_f32_dpp v55, v79, v88 row_newbcast:11 row_mask:0xf bank_mask:0xf
	v_fmac_f32_dpp v94, v83, v52 row_newbcast:8 row_mask:0xf bank_mask:0xf
	v_fmac_f32_dpp v95, v83, v53 row_newbcast:9 row_mask:0xf bank_mask:0xf
	v_fmac_f32_dpp v96, v83, v54 row_newbcast:10 row_mask:0xf bank_mask:0xf
	v_fmac_f32_dpp v97, v83, v55 row_newbcast:11 row_mask:0xf bank_mask:0xf
	v_mul_f32_dpp v48, v71, v48 row_newbcast:12 row_mask:0xf bank_mask:0xf
	v_mul_f32_dpp v49, v71, v49 row_newbcast:13 row_mask:0xf bank_mask:0xf
	v_mul_f32_dpp v50, v71, v50 row_newbcast:14 row_mask:0xf bank_mask:0xf
	v_mul_f32_dpp v51, v71, v51 row_newbcast:15 row_mask:0xf bank_mask:0xf
	v_fmac_f32_dpp v48, v75, v90 row_newbcast:12 row_mask:0xf bank_mask:0xf
	v_fmac_f32_dpp v49, v75, v90 row_newbcast:13 row_mask:0xf bank_mask:0xf
	v_fmac_f32_dpp v50, v75, v90 row_newbcast:14 row_mask:0xf bank_mask:0xf
	v_fmac_f32_dpp v51, v75, v90 row_newbcast:15 row_mask:0xf bank_mask:0xf
	v_fmac_f32_dpp v48, v79, v88 row_newbcast:12 row_mask:0xf bank_mask:0xf
	v_fmac_f32_dpp v49, v79, v88 row_newbcast:13 row_mask:0xf bank_mask:0xf
	v_fmac_f32_dpp v50, v79, v88 row_newbcast:14 row_mask:0xf bank_mask:0xf
	v_fmac_f32_dpp v51, v79, v88 row_newbcast:15 row_mask:0xf bank_mask:0xf
	v_fmac_f32_dpp v94, v83, v48 row_newbcast:12 row_mask:0xf bank_mask:0xf
	v_fmac_f32_dpp v95, v83, v49 row_newbcast:13 row_mask:0xf bank_mask:0xf
	v_fmac_f32_dpp v96, v83, v50 row_newbcast:14 row_mask:0xf bank_mask:0xf
	v_fmac_f32_dpp v97, v83, v51 row_newbcast:15 row_mask:0xf bank_mask:0xf
	ds_read_b32 v71, v100 offset:11712
	ds_read_b32 v75, v100 offset:16064
	ds_read_b32 v83, v100 offset:4544
	v_add_f32_e32 v94, v94, v95
	v_add_f32_e32 v96, v96, v97
	s_or_b32 s8, s14, s44
	s_ashr_i32 s9, s8, 31
	s_lshl_b64 s[8:9], s[8:9], 10
	v_add_f32_e32 v94, v94, v96
	s_add_i32 s4, s4, 1
	s_add_i32 s5, s5, -1
	v_lshl_add_u64 v[104:105], v[136:137], 0, s[8:9]
	v_cvt_pk_bf16_f32 v94, v94, v94
	s_cmp_eq_u32 s4, 16
	global_store_short v[104:105], v94, off
	s_cbranch_scc1 .Lscan_c_exit
	s_waitcnt vmcnt(1)
	v_mov_b32_e32 v76, v84
	v_mov_b32_e32 v77, v85
	v_mov_b32_e32 v78, v86
	v_mov_b32_e32 v79, v87
	v_mov_b32_e32 v88, v89
	s_branch .Lscan_c_step
